# removed per-phase s_setprio flips in the 8 GEMM K-loops (A/B of priority), on top of rstd prelude fix
# baseline (speedup 1.0000x reference)
.LBB0_220:
	ds_read_b128 v[148:151], v173
	ds_read_b128 v[152:155], v173 offset:1024
	ds_read_b128 v[156:159], v173 offset:2048
	ds_read_b128 v[160:163], v173 offset:3072
	ds_read_b128 v[164:167], v174
	ds_read_b128 v[180:183], v174 offset:1024
	ds_read_b128 v[184:187], v174 offset:2048
	ds_read_b128 v[188:191], v174 offset:3072
	s_add_u32 s52, s50, 0xfffc0080
	s_addc_u32 s53, s51, -1
	s_cmp_eq_u32 s66, 12
	s_cselect_b32 s55, s9, s53
	s_cselect_b32 s54, s11, s52
	s_cselect_b32 s53, s20, s45
	s_cselect_b32 s52, s33, s43
	v_lshl_add_u64 v[168:169], s[50:51], 0, v[140:141]
	s_add_i32 m0, s35, 0xc000
	ds_read_b128 v[192:195], v175
	ds_read_b128 v[196:199], v175 offset:1024
	ds_read_b128 v[204:207], v175 offset:2048
	ds_read_b128 v[208:211], v175 offset:3072
	ds_read_b128 v[212:215], v175 offset:4096
	ds_read_b128 v[216:219], v175 offset:5120
	ds_read_b128 v[220:223], v175 offset:6144
	ds_read_b128 v[224:227], v175 offset:7168
	global_load_lds_dwordx4 v[168:169], off
	v_lshl_add_u64 v[168:169], s[50:51], 0, v[142:143]
	s_add_i32 m0, s35, 0xe000
	s_nop 0
	global_load_lds_dwordx4 v[168:169], off
	s_waitcnt vmcnt(8)
	s_waitcnt lgkmcnt(0)
	s_barrier
	s_waitcnt lgkmcnt(0)
	v_mfma_f32_16x16x32_bf16 v[124:127], v[148:151], v[192:195], v[124:127]
	v_mfma_f32_16x16x32_bf16 v[120:123], v[156:159], v[192:195], v[120:123]
	v_mfma_f32_16x16x32_bf16 v[108:111], v[148:151], v[204:207], v[108:111]
	v_mfma_f32_16x16x32_bf16 v[104:107], v[156:159], v[204:207], v[104:107]
	v_mfma_f32_16x16x32_bf16 v[92:95], v[148:151], v[212:215], v[92:95]
	v_mfma_f32_16x16x32_bf16 v[88:91], v[156:159], v[212:215], v[88:91]
	v_mfma_f32_16x16x32_bf16 v[76:79], v[148:151], v[220:223], v[76:79]
	v_mfma_f32_16x16x32_bf16 v[72:75], v[156:159], v[220:223], v[72:75]
	v_mfma_f32_16x16x32_bf16 v[124:127], v[152:155], v[196:199], v[124:127]
	v_mfma_f32_16x16x32_bf16 v[120:123], v[160:163], v[196:199], v[120:123]
	v_mfma_f32_16x16x32_bf16 v[108:111], v[152:155], v[208:211], v[108:111]
	v_mfma_f32_16x16x32_bf16 v[104:107], v[160:163], v[208:211], v[104:107]
	v_mfma_f32_16x16x32_bf16 v[92:95], v[152:155], v[216:219], v[92:95]
	v_mfma_f32_16x16x32_bf16 v[88:91], v[160:163], v[216:219], v[88:91]
	v_mfma_f32_16x16x32_bf16 v[76:79], v[152:155], v[224:227], v[76:79]
	v_mfma_f32_16x16x32_bf16 v[72:75], v[160:163], v[224:227], v[72:75]
	v_mfma_f32_16x16x32_bf16 v[116:119], v[164:167], v[192:195], v[116:119]
	v_mfma_f32_16x16x32_bf16 v[112:115], v[184:187], v[192:195], v[112:115]
	v_mfma_f32_16x16x32_bf16 v[100:103], v[164:167], v[204:207], v[100:103]
	v_mfma_f32_16x16x32_bf16 v[96:99], v[184:187], v[204:207], v[96:99]
	v_mfma_f32_16x16x32_bf16 v[84:87], v[164:167], v[212:215], v[84:87]
	v_mfma_f32_16x16x32_bf16 v[80:83], v[184:187], v[212:215], v[80:83]
	v_mfma_f32_16x16x32_bf16 v[68:71], v[164:167], v[220:223], v[68:71]
	v_mfma_f32_16x16x32_bf16 v[64:67], v[184:187], v[220:223], v[64:67]
	v_mfma_f32_16x16x32_bf16 v[116:119], v[180:183], v[196:199], v[116:119]
	v_mfma_f32_16x16x32_bf16 v[112:115], v[188:191], v[196:199], v[112:115]
	v_mfma_f32_16x16x32_bf16 v[100:103], v[180:183], v[208:211], v[100:103]
	v_mfma_f32_16x16x32_bf16 v[96:99], v[188:191], v[208:211], v[96:99]
	v_mfma_f32_16x16x32_bf16 v[84:87], v[180:183], v[216:219], v[84:87]
	v_mfma_f32_16x16x32_bf16 v[80:83], v[188:191], v[216:219], v[80:83]
	v_mfma_f32_16x16x32_bf16 v[68:71], v[180:183], v[224:227], v[68:71]
	v_mfma_f32_16x16x32_bf16 v[64:67], v[188:191], v[224:227], v[64:67]
	s_barrier
	s_add_i32 s67, s63, s31
	v_lshl_add_u64 v[168:169], s[52:53], 0, v[130:131]
	s_mov_b32 m0, s67
	ds_read_b128 v[192:195], v175 offset:16384
	ds_read_b128 v[196:199], v175 offset:17408
	ds_read_b128 v[204:207], v175 offset:18432
	ds_read_b128 v[208:211], v175 offset:19456
	ds_read_b128 v[212:215], v175 offset:20480
	ds_read_b128 v[216:219], v175 offset:21504
	ds_read_b128 v[220:223], v175 offset:22528
	ds_read_b128 v[224:227], v175 offset:23552
	global_load_lds_dwordx4 v[168:169], off
	s_add_i32 m0, s67, 0x2000
	s_add_u32 s68, s52, 0x40000
	v_lshl_add_u64 v[200:201], s[52:53], 0, v[134:135]
	s_addc_u32 s69, s53, 0
	s_add_i32 s67, s64, s31
	global_load_lds_dwordx4 v[200:201], off
	v_lshl_add_u64 v[228:229], s[68:69], 0, v[130:131]
	s_mov_b32 m0, s67
	v_lshl_add_u64 v[230:231], s[54:55], 0, v[132:133]
	global_load_lds_dwordx4 v[228:229], off
	v_lshl_add_u64 v[228:229], s[68:69], 0, v[134:135]
	s_add_i32 m0, s67, 0x2000
	s_nop 0
	global_load_lds_dwordx4 v[228:229], off
	v_lshl_add_u64 v[228:229], s[54:55], 0, v[128:129]
	s_mov_b32 m0, s35
	s_nop 0
	global_load_lds_dwordx4 v[228:229], off
	s_mov_b32 m0, s37
	s_nop 0
	global_load_lds_dwordx4 v[230:231], off
	s_waitcnt vmcnt(8)
	s_waitcnt lgkmcnt(0)
	s_barrier
	s_waitcnt lgkmcnt(0)
	v_mfma_f32_16x16x32_bf16 v[60:63], v[148:151], v[192:195], v[60:63]
	v_mfma_f32_16x16x32_bf16 v[56:59], v[156:159], v[192:195], v[56:59]
	v_mfma_f32_16x16x32_bf16 v[44:47], v[148:151], v[204:207], v[44:47]
	v_mfma_f32_16x16x32_bf16 v[40:43], v[156:159], v[204:207], v[40:43]
	v_mfma_f32_16x16x32_bf16 v[28:31], v[148:151], v[212:215], v[28:31]
	v_mfma_f32_16x16x32_bf16 v[24:27], v[156:159], v[212:215], v[24:27]
	v_mfma_f32_16x16x32_bf16 v[12:15], v[148:151], v[220:223], v[12:15]
	v_mfma_f32_16x16x32_bf16 v[8:11], v[156:159], v[220:223], v[8:11]
	v_mfma_f32_16x16x32_bf16 v[60:63], v[152:155], v[196:199], v[60:63]
	v_mfma_f32_16x16x32_bf16 v[56:59], v[160:163], v[196:199], v[56:59]
	v_mfma_f32_16x16x32_bf16 v[44:47], v[152:155], v[208:211], v[44:47]
	v_mfma_f32_16x16x32_bf16 v[40:43], v[160:163], v[208:211], v[40:43]
	v_mfma_f32_16x16x32_bf16 v[28:31], v[152:155], v[216:219], v[28:31]
	v_mfma_f32_16x16x32_bf16 v[24:27], v[160:163], v[216:219], v[24:27]
	v_mfma_f32_16x16x32_bf16 v[12:15], v[152:155], v[224:227], v[12:15]
	v_mfma_f32_16x16x32_bf16 v[8:11], v[160:163], v[224:227], v[8:11]
	v_mfma_f32_16x16x32_bf16 v[52:55], v[164:167], v[192:195], v[52:55]
	v_mfma_f32_16x16x32_bf16 v[48:51], v[184:187], v[192:195], v[48:51]
	v_mfma_f32_16x16x32_bf16 v[36:39], v[164:167], v[204:207], v[36:39]
	v_mfma_f32_16x16x32_bf16 v[32:35], v[184:187], v[204:207], v[32:35]
	v_mfma_f32_16x16x32_bf16 v[20:23], v[164:167], v[212:215], v[20:23]
	v_mfma_f32_16x16x32_bf16 v[16:19], v[184:187], v[212:215], v[16:19]
	v_mfma_f32_16x16x32_bf16 v[4:7], v[164:167], v[220:223], v[4:7]
	v_mfma_f32_16x16x32_bf16 v[0:3], v[184:187], v[220:223], v[0:3]
	v_mfma_f32_16x16x32_bf16 v[52:55], v[180:183], v[196:199], v[52:55]
	v_mfma_f32_16x16x32_bf16 v[48:51], v[188:191], v[196:199], v[48:51]
	v_mfma_f32_16x16x32_bf16 v[36:39], v[180:183], v[208:211], v[36:39]
	v_mfma_f32_16x16x32_bf16 v[32:35], v[188:191], v[208:211], v[32:35]
	v_mfma_f32_16x16x32_bf16 v[20:23], v[180:183], v[216:219], v[20:23]
	v_mfma_f32_16x16x32_bf16 v[16:19], v[188:191], v[216:219], v[16:19]
	v_mfma_f32_16x16x32_bf16 v[4:7], v[180:183], v[224:227], v[4:7]
	v_mfma_f32_16x16x32_bf16 v[0:3], v[188:191], v[224:227], v[0:3]
	s_barrier
	s_add_i32 s67, 0, 0x18000
	v_add_u32_e32 v137, s67, v171
	s_add_i32 s68, 0, 0x1c000
	ds_read_b128 v[148:151], v137
	ds_read_b128 v[152:155], v137 offset:1024
	ds_read_b128 v[156:159], v137 offset:2048
	ds_read_b128 v[160:163], v137 offset:3072
	v_add_u32_e32 v137, s68, v171
	ds_read_b128 v[164:167], v137
	ds_read_b128 v[180:183], v137 offset:1024
	ds_read_b128 v[184:187], v137 offset:2048
	ds_read_b128 v[188:191], v137 offset:3072
	s_add_u32 s54, s54, 0x40000
	s_addc_u32 s55, s55, 0
	s_mov_b32 m0, s39
	v_lshl_add_u64 v[232:233], s[54:55], 0, v[128:129]
	ds_read_b128 v[192:195], v175 offset:32768
	ds_read_b128 v[196:199], v175 offset:33792
	ds_read_b128 v[204:207], v175 offset:34816
	ds_read_b128 v[208:211], v175 offset:35840
	ds_read_b128 v[212:215], v175 offset:36864
	ds_read_b128 v[216:219], v175 offset:37888
	ds_read_b128 v[220:223], v175 offset:38912
	ds_read_b128 v[224:227], v175 offset:39936
	global_load_lds_dwordx4 v[232:233], off
	v_lshl_add_u64 v[232:233], s[54:55], 0, v[132:133]
	s_mov_b32 m0, s41
	s_nop 0
	global_load_lds_dwordx4 v[232:233], off
	s_waitcnt vmcnt(8)
	s_waitcnt lgkmcnt(0)
	s_barrier
	s_waitcnt lgkmcnt(0)
	v_mfma_f32_16x16x32_bf16 v[124:127], v[148:151], v[192:195], v[124:127]
	v_mfma_f32_16x16x32_bf16 v[120:123], v[156:159], v[192:195], v[120:123]
	v_mfma_f32_16x16x32_bf16 v[108:111], v[148:151], v[204:207], v[108:111]
	v_mfma_f32_16x16x32_bf16 v[104:107], v[156:159], v[204:207], v[104:107]
	v_mfma_f32_16x16x32_bf16 v[92:95], v[148:151], v[212:215], v[92:95]
	v_mfma_f32_16x16x32_bf16 v[88:91], v[156:159], v[212:215], v[88:91]
	v_mfma_f32_16x16x32_bf16 v[76:79], v[148:151], v[220:223], v[76:79]
	v_mfma_f32_16x16x32_bf16 v[72:75], v[156:159], v[220:223], v[72:75]
	v_mfma_f32_16x16x32_bf16 v[124:127], v[152:155], v[196:199], v[124:127]
	v_mfma_f32_16x16x32_bf16 v[120:123], v[160:163], v[196:199], v[120:123]
	v_mfma_f32_16x16x32_bf16 v[108:111], v[152:155], v[208:211], v[108:111]
	v_mfma_f32_16x16x32_bf16 v[104:107], v[160:163], v[208:211], v[104:107]
	v_mfma_f32_16x16x32_bf16 v[92:95], v[152:155], v[216:219], v[92:95]
	v_mfma_f32_16x16x32_bf16 v[88:91], v[160:163], v[216:219], v[88:91]
	v_mfma_f32_16x16x32_bf16 v[76:79], v[152:155], v[224:227], v[76:79]
	v_mfma_f32_16x16x32_bf16 v[72:75], v[160:163], v[224:227], v[72:75]
	v_mfma_f32_16x16x32_bf16 v[116:119], v[164:167], v[192:195], v[116:119]
	v_mfma_f32_16x16x32_bf16 v[112:115], v[184:187], v[192:195], v[112:115]
	v_mfma_f32_16x16x32_bf16 v[100:103], v[164:167], v[204:207], v[100:103]
	v_mfma_f32_16x16x32_bf16 v[96:99], v[184:187], v[204:207], v[96:99]
	v_mfma_f32_16x16x32_bf16 v[84:87], v[164:167], v[212:215], v[84:87]
	v_mfma_f32_16x16x32_bf16 v[80:83], v[184:187], v[212:215], v[80:83]
	v_mfma_f32_16x16x32_bf16 v[68:71], v[164:167], v[220:223], v[68:71]
	v_mfma_f32_16x16x32_bf16 v[64:67], v[184:187], v[220:223], v[64:67]
	v_mfma_f32_16x16x32_bf16 v[116:119], v[180:183], v[196:199], v[116:119]
	v_mfma_f32_16x16x32_bf16 v[112:115], v[188:191], v[196:199], v[112:115]
	v_mfma_f32_16x16x32_bf16 v[100:103], v[180:183], v[208:211], v[100:103]
	v_mfma_f32_16x16x32_bf16 v[96:99], v[188:191], v[208:211], v[96:99]
	v_mfma_f32_16x16x32_bf16 v[84:87], v[180:183], v[216:219], v[84:87]
	v_mfma_f32_16x16x32_bf16 v[80:83], v[188:191], v[216:219], v[80:83]
	v_mfma_f32_16x16x32_bf16 v[68:71], v[180:183], v[224:227], v[68:71]
	v_mfma_f32_16x16x32_bf16 v[64:67], v[188:191], v[224:227], v[64:67]
	s_barrier
	s_add_i32 s54, s67, s31
	v_lshl_add_u64 v[168:169], v[168:169], 0, s[22:23]
	s_mov_b32 m0, s54
	ds_read_b128 v[192:195], v175 offset:49152
	ds_read_b128 v[196:199], v175 offset:50176
	ds_read_b128 v[204:207], v175 offset:51200
	ds_read_b128 v[208:211], v175 offset:52224
	ds_read_b128 v[212:215], v175 offset:53248
	ds_read_b128 v[216:219], v175 offset:54272
	ds_read_b128 v[220:223], v175 offset:55296
	ds_read_b128 v[224:227], v175 offset:56320
	global_load_lds_dwordx4 v[168:169], off
	s_add_i32 m0, s54, 0x2000
	s_add_u32 s52, s52, 0x40080
	v_lshl_add_u64 v[168:169], v[200:201], 0, s[22:23]
	s_addc_u32 s53, s53, 0
	s_add_i32 s54, s68, s31
	global_load_lds_dwordx4 v[168:169], off
	v_lshl_add_u64 v[168:169], s[52:53], 0, v[130:131]
	s_mov_b32 m0, s54
	s_nop 0
	global_load_lds_dwordx4 v[168:169], off
	v_lshl_add_u64 v[168:169], s[52:53], 0, v[134:135]
	s_add_i32 m0, s54, 0x2000
	s_nop 0
	global_load_lds_dwordx4 v[168:169], off
	v_lshl_add_u64 v[168:169], v[228:229], 0, s[22:23]
	s_mov_b32 m0, s60
	s_nop 0
	global_load_lds_dwordx4 v[168:169], off
	v_lshl_add_u64 v[168:169], v[230:231], 0, s[22:23]
	s_mov_b32 m0, s61
	s_nop 0
	global_load_lds_dwordx4 v[168:169], off
	s_waitcnt vmcnt(8)
	s_waitcnt lgkmcnt(0)
	s_barrier
	s_waitcnt lgkmcnt(0)
	v_mfma_f32_16x16x32_bf16 v[60:63], v[148:151], v[192:195], v[60:63]
	v_mfma_f32_16x16x32_bf16 v[56:59], v[156:159], v[192:195], v[56:59]
	v_mfma_f32_16x16x32_bf16 v[44:47], v[148:151], v[204:207], v[44:47]
	v_mfma_f32_16x16x32_bf16 v[40:43], v[156:159], v[204:207], v[40:43]
	v_mfma_f32_16x16x32_bf16 v[28:31], v[148:151], v[212:215], v[28:31]
	v_mfma_f32_16x16x32_bf16 v[24:27], v[156:159], v[212:215], v[24:27]
	v_mfma_f32_16x16x32_bf16 v[12:15], v[148:151], v[220:223], v[12:15]
	v_mfma_f32_16x16x32_bf16 v[8:11], v[156:159], v[220:223], v[8:11]
	v_mfma_f32_16x16x32_bf16 v[60:63], v[152:155], v[196:199], v[60:63]
	v_mfma_f32_16x16x32_bf16 v[56:59], v[160:163], v[196:199], v[56:59]
	v_mfma_f32_16x16x32_bf16 v[44:47], v[152:155], v[208:211], v[44:47]
	v_mfma_f32_16x16x32_bf16 v[40:43], v[160:163], v[208:211], v[40:43]
	v_mfma_f32_16x16x32_bf16 v[28:31], v[152:155], v[216:219], v[28:31]
	v_mfma_f32_16x16x32_bf16 v[24:27], v[160:163], v[216:219], v[24:27]
	v_mfma_f32_16x16x32_bf16 v[12:15], v[152:155], v[224:227], v[12:15]
	v_mfma_f32_16x16x32_bf16 v[8:11], v[160:163], v[224:227], v[8:11]
	v_mfma_f32_16x16x32_bf16 v[52:55], v[164:167], v[192:195], v[52:55]
	v_mfma_f32_16x16x32_bf16 v[48:51], v[184:187], v[192:195], v[48:51]
	v_mfma_f32_16x16x32_bf16 v[36:39], v[164:167], v[204:207], v[36:39]
	v_mfma_f32_16x16x32_bf16 v[32:35], v[184:187], v[204:207], v[32:35]
	v_mfma_f32_16x16x32_bf16 v[20:23], v[164:167], v[212:215], v[20:23]
	v_mfma_f32_16x16x32_bf16 v[16:19], v[184:187], v[212:215], v[16:19]
	v_mfma_f32_16x16x32_bf16 v[4:7], v[164:167], v[220:223], v[4:7]
	v_mfma_f32_16x16x32_bf16 v[0:3], v[184:187], v[220:223], v[0:3]
	v_mfma_f32_16x16x32_bf16 v[52:55], v[180:183], v[196:199], v[52:55]
	v_mfma_f32_16x16x32_bf16 v[48:51], v[188:191], v[196:199], v[48:51]
	v_mfma_f32_16x16x32_bf16 v[36:39], v[180:183], v[208:211], v[36:39]
	v_mfma_f32_16x16x32_bf16 v[32:35], v[188:191], v[208:211], v[32:35]
	v_mfma_f32_16x16x32_bf16 v[20:23], v[180:183], v[216:219], v[20:23]
	v_mfma_f32_16x16x32_bf16 v[16:19], v[188:191], v[216:219], v[16:19]
	v_mfma_f32_16x16x32_bf16 v[4:7], v[180:183], v[224:227], v[4:7]
	v_mfma_f32_16x16x32_bf16 v[0:3], v[188:191], v[224:227], v[0:3]
	s_barrier
	s_add_i32 s66, s66, 2
	s_add_u32 s50, s50, 0x100
	s_addc_u32 s51, s51, 0
	s_add_u32 s43, s43, 0x100
	s_addc_u32 s45, s45, 0
	s_cmp_gt_u32 s66, 13
	s_cbranch_scc0 .LBB0_220
	s_and_b64 vcc, exec, s[24:25]
	s_cbranch_vccz .LBB0_223
	s_barrier

.LBB0_401:
	ds_read_b128 v[128:131], v189
	ds_read_b128 v[132:135], v189 offset:1024
	ds_read_b128 v[136:139], v189 offset:2048
	ds_read_b128 v[140:143], v189 offset:3072
	ds_read_b128 v[144:147], v190
	ds_read_b128 v[148:151], v190 offset:1024
	ds_read_b128 v[168:171], v190 offset:2048
	ds_read_b128 v[172:175], v190 offset:3072
	s_add_u32 s4, s42, 0xfff80080
	s_addc_u32 s5, s43, -1
	s_cmp_eq_u32 s59, 28
	s_cselect_b32 s45, s35, s5
	s_cselect_b32 s44, s41, s4
	s_cselect_b32 s5, s31, s58
	s_cselect_b32 s4, s56, s57
	v_lshl_add_u64 v[184:185], s[42:43], 0, v[160:161]
	s_add_i32 m0, s47, 0xc000
	ds_read_b128 v[176:179], v191
	ds_read_b128 v[180:183], v191 offset:1024
	ds_read_b128 v[194:197], v191 offset:2048
	ds_read_b128 v[198:201], v191 offset:3072
	ds_read_b128 v[204:207], v191 offset:4096
	ds_read_b128 v[208:211], v191 offset:5120
	ds_read_b128 v[212:215], v191 offset:6144
	ds_read_b128 v[216:219], v191 offset:7168
	global_load_lds_dwordx4 v[184:185], off
	v_lshl_add_u64 v[184:185], s[42:43], 0, v[162:163]
	s_add_i32 m0, s47, 0xe000
	s_nop 0
	global_load_lds_dwordx4 v[184:185], off
	s_waitcnt vmcnt(8)
	s_waitcnt lgkmcnt(0)
	s_barrier
	s_waitcnt lgkmcnt(0)
	v_mfma_f32_16x16x32_bf16 v[124:127], v[128:131], v[176:179], v[124:127]
	v_mfma_f32_16x16x32_bf16 v[120:123], v[136:139], v[176:179], v[120:123]
	v_mfma_f32_16x16x32_bf16 v[108:111], v[128:131], v[194:197], v[108:111]
	v_mfma_f32_16x16x32_bf16 v[104:107], v[136:139], v[194:197], v[104:107]
	v_mfma_f32_16x16x32_bf16 v[92:95], v[128:131], v[204:207], v[92:95]
	v_mfma_f32_16x16x32_bf16 v[88:91], v[136:139], v[204:207], v[88:91]
	v_mfma_f32_16x16x32_bf16 v[76:79], v[128:131], v[212:215], v[76:79]
	v_mfma_f32_16x16x32_bf16 v[72:75], v[136:139], v[212:215], v[72:75]
	v_mfma_f32_16x16x32_bf16 v[124:127], v[132:135], v[180:183], v[124:127]
	v_mfma_f32_16x16x32_bf16 v[120:123], v[140:143], v[180:183], v[120:123]
	v_mfma_f32_16x16x32_bf16 v[108:111], v[132:135], v[198:201], v[108:111]
	v_mfma_f32_16x16x32_bf16 v[104:107], v[140:143], v[198:201], v[104:107]
	v_mfma_f32_16x16x32_bf16 v[92:95], v[132:135], v[208:211], v[92:95]
	v_mfma_f32_16x16x32_bf16 v[88:91], v[140:143], v[208:211], v[88:91]
	v_mfma_f32_16x16x32_bf16 v[76:79], v[132:135], v[216:219], v[76:79]
	v_mfma_f32_16x16x32_bf16 v[72:75], v[140:143], v[216:219], v[72:75]
	v_mfma_f32_16x16x32_bf16 v[116:119], v[144:147], v[176:179], v[116:119]
	v_mfma_f32_16x16x32_bf16 v[112:115], v[168:171], v[176:179], v[112:115]
	v_mfma_f32_16x16x32_bf16 v[100:103], v[144:147], v[194:197], v[100:103]
	v_mfma_f32_16x16x32_bf16 v[96:99], v[168:171], v[194:197], v[96:99]
	v_mfma_f32_16x16x32_bf16 v[84:87], v[144:147], v[204:207], v[84:87]
	v_mfma_f32_16x16x32_bf16 v[80:83], v[168:171], v[204:207], v[80:83]
	v_mfma_f32_16x16x32_bf16 v[68:71], v[144:147], v[212:215], v[68:71]
	v_mfma_f32_16x16x32_bf16 v[64:67], v[168:171], v[212:215], v[64:67]
	v_mfma_f32_16x16x32_bf16 v[116:119], v[148:151], v[180:183], v[116:119]
	v_mfma_f32_16x16x32_bf16 v[112:115], v[172:175], v[180:183], v[112:115]
	v_mfma_f32_16x16x32_bf16 v[100:103], v[148:151], v[198:201], v[100:103]
	v_mfma_f32_16x16x32_bf16 v[96:99], v[172:175], v[198:201], v[96:99]
	v_mfma_f32_16x16x32_bf16 v[84:87], v[148:151], v[208:211], v[84:87]
	v_mfma_f32_16x16x32_bf16 v[80:83], v[172:175], v[208:211], v[80:83]
	v_mfma_f32_16x16x32_bf16 v[68:71], v[148:151], v[216:219], v[68:71]
	v_mfma_f32_16x16x32_bf16 v[64:67], v[172:175], v[216:219], v[64:67]
	s_barrier
	s_add_i32 s60, s53, s46
	v_lshl_add_u64 v[184:185], s[4:5], 0, v[154:155]
	s_mov_b32 m0, s60
	ds_read_b128 v[176:179], v191 offset:16384
	ds_read_b128 v[180:183], v191 offset:17408
	ds_read_b128 v[194:197], v191 offset:18432
	ds_read_b128 v[198:201], v191 offset:19456
	ds_read_b128 v[204:207], v191 offset:20480
	ds_read_b128 v[208:211], v191 offset:21504
	ds_read_b128 v[212:215], v191 offset:22528
	ds_read_b128 v[216:219], v191 offset:23552
	global_load_lds_dwordx4 v[184:185], off
	s_add_i32 m0, s60, 0x2000
	s_add_u32 s60, s4, 0x80000
	v_lshl_add_u64 v[220:221], s[4:5], 0, v[158:159]
	s_addc_u32 s61, s5, 0
	s_add_i32 s62, s54, s46
	global_load_lds_dwordx4 v[220:221], off
	v_lshl_add_u64 v[222:223], s[60:61], 0, v[154:155]
	s_mov_b32 m0, s62
	v_lshl_add_u64 v[224:225], s[44:45], 0, v[156:157]
	global_load_lds_dwordx4 v[222:223], off
	v_lshl_add_u64 v[222:223], s[60:61], 0, v[158:159]
	s_add_i32 m0, s62, 0x2000
	s_nop 0
	global_load_lds_dwordx4 v[222:223], off
	v_lshl_add_u64 v[222:223], s[44:45], 0, v[152:153]
	s_mov_b32 m0, s47
	s_nop 0
	global_load_lds_dwordx4 v[222:223], off
	s_mov_b32 m0, s48
	s_nop 0
	global_load_lds_dwordx4 v[224:225], off
	s_waitcnt vmcnt(8)
	s_waitcnt lgkmcnt(0)
	s_barrier
	s_waitcnt lgkmcnt(0)
	v_mfma_f32_16x16x32_bf16 v[60:63], v[128:131], v[176:179], v[60:63]
	v_mfma_f32_16x16x32_bf16 v[56:59], v[136:139], v[176:179], v[56:59]
	v_mfma_f32_16x16x32_bf16 v[44:47], v[128:131], v[194:197], v[44:47]
	v_mfma_f32_16x16x32_bf16 v[40:43], v[136:139], v[194:197], v[40:43]
	v_mfma_f32_16x16x32_bf16 v[28:31], v[128:131], v[204:207], v[28:31]
	v_mfma_f32_16x16x32_bf16 v[24:27], v[136:139], v[204:207], v[24:27]
	v_mfma_f32_16x16x32_bf16 v[12:15], v[128:131], v[212:215], v[12:15]
	v_mfma_f32_16x16x32_bf16 v[8:11], v[136:139], v[212:215], v[8:11]
	v_mfma_f32_16x16x32_bf16 v[60:63], v[132:135], v[180:183], v[60:63]
	v_mfma_f32_16x16x32_bf16 v[56:59], v[140:143], v[180:183], v[56:59]
	v_mfma_f32_16x16x32_bf16 v[44:47], v[132:135], v[198:201], v[44:47]
	v_mfma_f32_16x16x32_bf16 v[40:43], v[140:143], v[198:201], v[40:43]
	v_mfma_f32_16x16x32_bf16 v[28:31], v[132:135], v[208:211], v[28:31]
	v_mfma_f32_16x16x32_bf16 v[24:27], v[140:143], v[208:211], v[24:27]
	v_mfma_f32_16x16x32_bf16 v[12:15], v[132:135], v[216:219], v[12:15]
	v_mfma_f32_16x16x32_bf16 v[8:11], v[140:143], v[216:219], v[8:11]
	v_mfma_f32_16x16x32_bf16 v[52:55], v[144:147], v[176:179], v[52:55]
	v_mfma_f32_16x16x32_bf16 v[48:51], v[168:171], v[176:179], v[48:51]
	v_mfma_f32_16x16x32_bf16 v[36:39], v[144:147], v[194:197], v[36:39]
	v_mfma_f32_16x16x32_bf16 v[32:35], v[168:171], v[194:197], v[32:35]
	v_mfma_f32_16x16x32_bf16 v[20:23], v[144:147], v[204:207], v[20:23]
	v_mfma_f32_16x16x32_bf16 v[16:19], v[168:171], v[204:207], v[16:19]
	v_mfma_f32_16x16x32_bf16 v[4:7], v[144:147], v[212:215], v[4:7]
	v_mfma_f32_16x16x32_bf16 v[0:3], v[168:171], v[212:215], v[0:3]
	v_mfma_f32_16x16x32_bf16 v[52:55], v[148:151], v[180:183], v[52:55]
	v_mfma_f32_16x16x32_bf16 v[48:51], v[172:175], v[180:183], v[48:51]
	v_mfma_f32_16x16x32_bf16 v[36:39], v[148:151], v[198:201], v[36:39]
	v_mfma_f32_16x16x32_bf16 v[32:35], v[172:175], v[198:201], v[32:35]
	v_mfma_f32_16x16x32_bf16 v[20:23], v[148:151], v[208:211], v[20:23]
	v_mfma_f32_16x16x32_bf16 v[16:19], v[172:175], v[208:211], v[16:19]
	v_mfma_f32_16x16x32_bf16 v[4:7], v[148:151], v[216:219], v[4:7]
	v_mfma_f32_16x16x32_bf16 v[0:3], v[172:175], v[216:219], v[0:3]
	s_barrier
	s_add_i32 s60, 0, 0x18000
	s_add_i32 s61, 0, 0x1c000
	v_add_u32_e32 v140, s60, v187
	v_add_u32_e32 v172, s61, v187
	ds_read_b128 v[128:131], v140
	ds_read_b128 v[132:135], v140 offset:1024
	ds_read_b128 v[136:139], v140 offset:2048
	ds_read_b128 v[140:143], v140 offset:3072
	ds_read_b128 v[144:147], v172
	ds_read_b128 v[148:151], v172 offset:1024
	ds_read_b128 v[168:171], v172 offset:2048
	ds_read_b128 v[172:175], v172 offset:3072
	s_add_u32 s44, s44, 0x80000
	s_addc_u32 s45, s45, 0
	s_mov_b32 m0, s49
	v_lshl_add_u64 v[226:227], s[44:45], 0, v[152:153]
	ds_read_b128 v[176:179], v191 offset:32768
	ds_read_b128 v[180:183], v191 offset:33792
	ds_read_b128 v[194:197], v191 offset:34816
	ds_read_b128 v[198:201], v191 offset:35840
	ds_read_b128 v[204:207], v191 offset:36864
	ds_read_b128 v[208:211], v191 offset:37888
	ds_read_b128 v[212:215], v191 offset:38912
	ds_read_b128 v[216:219], v191 offset:39936
	global_load_lds_dwordx4 v[226:227], off
	v_lshl_add_u64 v[226:227], s[44:45], 0, v[156:157]
	s_mov_b32 m0, s50
	s_nop 0
	global_load_lds_dwordx4 v[226:227], off
	s_waitcnt vmcnt(8)
	s_waitcnt lgkmcnt(0)
	s_barrier
	s_waitcnt lgkmcnt(0)
	v_mfma_f32_16x16x32_bf16 v[124:127], v[128:131], v[176:179], v[124:127]
	v_mfma_f32_16x16x32_bf16 v[120:123], v[136:139], v[176:179], v[120:123]
	v_mfma_f32_16x16x32_bf16 v[108:111], v[128:131], v[194:197], v[108:111]
	v_mfma_f32_16x16x32_bf16 v[104:107], v[136:139], v[194:197], v[104:107]
	v_mfma_f32_16x16x32_bf16 v[92:95], v[128:131], v[204:207], v[92:95]
	v_mfma_f32_16x16x32_bf16 v[88:91], v[136:139], v[204:207], v[88:91]
	v_mfma_f32_16x16x32_bf16 v[76:79], v[128:131], v[212:215], v[76:79]
	v_mfma_f32_16x16x32_bf16 v[72:75], v[136:139], v[212:215], v[72:75]
	v_mfma_f32_16x16x32_bf16 v[124:127], v[132:135], v[180:183], v[124:127]
	v_mfma_f32_16x16x32_bf16 v[120:123], v[140:143], v[180:183], v[120:123]
	v_mfma_f32_16x16x32_bf16 v[108:111], v[132:135], v[198:201], v[108:111]
	v_mfma_f32_16x16x32_bf16 v[104:107], v[140:143], v[198:201], v[104:107]
	v_mfma_f32_16x16x32_bf16 v[92:95], v[132:135], v[208:211], v[92:95]
	v_mfma_f32_16x16x32_bf16 v[88:91], v[140:143], v[208:211], v[88:91]
	v_mfma_f32_16x16x32_bf16 v[76:79], v[132:135], v[216:219], v[76:79]
	v_mfma_f32_16x16x32_bf16 v[72:75], v[140:143], v[216:219], v[72:75]
	v_mfma_f32_16x16x32_bf16 v[116:119], v[144:147], v[176:179], v[116:119]
	v_mfma_f32_16x16x32_bf16 v[112:115], v[168:171], v[176:179], v[112:115]
	v_mfma_f32_16x16x32_bf16 v[100:103], v[144:147], v[194:197], v[100:103]
	v_mfma_f32_16x16x32_bf16 v[96:99], v[168:171], v[194:197], v[96:99]
	v_mfma_f32_16x16x32_bf16 v[84:87], v[144:147], v[204:207], v[84:87]
	v_mfma_f32_16x16x32_bf16 v[80:83], v[168:171], v[204:207], v[80:83]
	v_mfma_f32_16x16x32_bf16 v[68:71], v[144:147], v[212:215], v[68:71]
	v_mfma_f32_16x16x32_bf16 v[64:67], v[168:171], v[212:215], v[64:67]
	v_mfma_f32_16x16x32_bf16 v[116:119], v[148:151], v[180:183], v[116:119]
	v_mfma_f32_16x16x32_bf16 v[112:115], v[172:175], v[180:183], v[112:115]
	v_mfma_f32_16x16x32_bf16 v[100:103], v[148:151], v[198:201], v[100:103]
	v_mfma_f32_16x16x32_bf16 v[96:99], v[172:175], v[198:201], v[96:99]
	v_mfma_f32_16x16x32_bf16 v[84:87], v[148:151], v[208:211], v[84:87]
	v_mfma_f32_16x16x32_bf16 v[80:83], v[172:175], v[208:211], v[80:83]
	v_mfma_f32_16x16x32_bf16 v[68:71], v[148:151], v[216:219], v[68:71]
	v_mfma_f32_16x16x32_bf16 v[64:67], v[172:175], v[216:219], v[64:67]
	s_barrier
	s_add_i32 s44, s60, s46
	v_lshl_add_u64 v[184:185], v[184:185], 0, s[26:27]
	s_mov_b32 m0, s44
	ds_read_b128 v[176:179], v191 offset:49152
	ds_read_b128 v[180:183], v191 offset:50176
	ds_read_b128 v[194:197], v191 offset:51200
	ds_read_b128 v[198:201], v191 offset:52224
	ds_read_b128 v[204:207], v191 offset:53248
	ds_read_b128 v[208:211], v191 offset:54272
	ds_read_b128 v[212:215], v191 offset:55296
	ds_read_b128 v[216:219], v191 offset:56320
	global_load_lds_dwordx4 v[184:185], off
	s_add_i32 m0, s44, 0x2000
	s_add_u32 s4, s4, 0x80080
	v_lshl_add_u64 v[184:185], v[220:221], 0, s[26:27]
	s_addc_u32 s5, s5, 0
	s_add_i32 s44, s61, s46
	global_load_lds_dwordx4 v[184:185], off
	v_lshl_add_u64 v[184:185], s[4:5], 0, v[154:155]
	s_mov_b32 m0, s44
	s_nop 0
	global_load_lds_dwordx4 v[184:185], off
	v_lshl_add_u64 v[184:185], s[4:5], 0, v[158:159]
	s_add_i32 m0, s44, 0x2000
	s_nop 0
	global_load_lds_dwordx4 v[184:185], off
	v_lshl_add_u64 v[184:185], v[222:223], 0, s[26:27]
	s_mov_b32 m0, s33
	s_nop 0
	global_load_lds_dwordx4 v[184:185], off
	v_lshl_add_u64 v[184:185], v[224:225], 0, s[26:27]
	s_mov_b32 m0, s52
	s_nop 0
	global_load_lds_dwordx4 v[184:185], off
	s_waitcnt vmcnt(8)
	s_waitcnt lgkmcnt(0)
	s_barrier
	s_waitcnt lgkmcnt(0)
	v_mfma_f32_16x16x32_bf16 v[60:63], v[128:131], v[176:179], v[60:63]
	v_mfma_f32_16x16x32_bf16 v[56:59], v[136:139], v[176:179], v[56:59]
	v_mfma_f32_16x16x32_bf16 v[44:47], v[128:131], v[194:197], v[44:47]
	v_mfma_f32_16x16x32_bf16 v[40:43], v[136:139], v[194:197], v[40:43]
	v_mfma_f32_16x16x32_bf16 v[28:31], v[128:131], v[204:207], v[28:31]
	v_mfma_f32_16x16x32_bf16 v[24:27], v[136:139], v[204:207], v[24:27]
	v_mfma_f32_16x16x32_bf16 v[12:15], v[128:131], v[212:215], v[12:15]
	v_mfma_f32_16x16x32_bf16 v[8:11], v[136:139], v[212:215], v[8:11]
	v_mfma_f32_16x16x32_bf16 v[60:63], v[132:135], v[180:183], v[60:63]
	v_mfma_f32_16x16x32_bf16 v[56:59], v[140:143], v[180:183], v[56:59]
	v_mfma_f32_16x16x32_bf16 v[44:47], v[132:135], v[198:201], v[44:47]
	v_mfma_f32_16x16x32_bf16 v[40:43], v[140:143], v[198:201], v[40:43]
	v_mfma_f32_16x16x32_bf16 v[28:31], v[132:135], v[208:211], v[28:31]
	v_mfma_f32_16x16x32_bf16 v[24:27], v[140:143], v[208:211], v[24:27]
	v_mfma_f32_16x16x32_bf16 v[12:15], v[132:135], v[216:219], v[12:15]
	v_mfma_f32_16x16x32_bf16 v[8:11], v[140:143], v[216:219], v[8:11]
	v_mfma_f32_16x16x32_bf16 v[52:55], v[144:147], v[176:179], v[52:55]
	v_mfma_f32_16x16x32_bf16 v[48:51], v[168:171], v[176:179], v[48:51]
	v_mfma_f32_16x16x32_bf16 v[36:39], v[144:147], v[194:197], v[36:39]
	v_mfma_f32_16x16x32_bf16 v[32:35], v[168:171], v[194:197], v[32:35]
	v_mfma_f32_16x16x32_bf16 v[20:23], v[144:147], v[204:207], v[20:23]
	v_mfma_f32_16x16x32_bf16 v[16:19], v[168:171], v[204:207], v[16:19]
	v_mfma_f32_16x16x32_bf16 v[4:7], v[144:147], v[212:215], v[4:7]
	v_mfma_f32_16x16x32_bf16 v[0:3], v[168:171], v[212:215], v[0:3]
	v_mfma_f32_16x16x32_bf16 v[52:55], v[148:151], v[180:183], v[52:55]
	v_mfma_f32_16x16x32_bf16 v[48:51], v[172:175], v[180:183], v[48:51]
	v_mfma_f32_16x16x32_bf16 v[36:39], v[148:151], v[198:201], v[36:39]
	v_mfma_f32_16x16x32_bf16 v[32:35], v[172:175], v[198:201], v[32:35]
	v_mfma_f32_16x16x32_bf16 v[20:23], v[148:151], v[208:211], v[20:23]
	v_mfma_f32_16x16x32_bf16 v[16:19], v[172:175], v[208:211], v[16:19]
	v_mfma_f32_16x16x32_bf16 v[4:7], v[148:151], v[216:219], v[4:7]
	v_mfma_f32_16x16x32_bf16 v[0:3], v[172:175], v[216:219], v[0:3]
	s_barrier
	s_add_i32 s59, s59, 2
	s_add_u32 s42, s42, 0x100
	s_addc_u32 s43, s43, 0
	s_add_u32 s57, s57, 0x100
	s_addc_u32 s58, s58, 0
	s_cmp_gt_u32 s59, 29
	s_cbranch_scc0 .LBB0_401
	s_and_b64 vcc, exec, s[28:29]
	s_cbranch_vccz .LBB0_404
	s_barrier

.LBB0_483:
	ds_read_b128 v[146:149], v169
	ds_read_b128 v[150:153], v169 offset:1024
	ds_read_b128 v[154:157], v169 offset:2048
	ds_read_b128 v[160:163], v169 offset:3072
	ds_read_b128 v[180:183], v171
	ds_read_b128 v[184:187], v171 offset:1024
	ds_read_b128 v[188:191], v171 offset:2048
	ds_read_b128 v[192:195], v171 offset:3072
	s_add_u32 s4, s10, 0xfffc0080
	s_addc_u32 s5, s11, -1
	s_cmp_eq_u32 s56, 12
	s_cselect_b32 s13, s9, s5
	s_cselect_b32 s12, s37, s4
	s_cselect_b32 s5, s35, s55
	s_cselect_b32 s4, s53, s54
	v_lshl_add_u64 v[200:201], s[10:11], 0, v[138:139]
	s_add_i32 m0, s42, 0xc000
	ds_read_b128 v[196:199], v173
	ds_read_b128 v[204:207], v173 offset:1024
	ds_read_b128 v[208:211], v173 offset:2048
	ds_read_b128 v[212:215], v173 offset:3072
	ds_read_b128 v[216:219], v173 offset:4096
	ds_read_b128 v[220:223], v173 offset:5120
	ds_read_b128 v[224:227], v173 offset:6144
	ds_read_b128 v[228:231], v173 offset:7168
	global_load_lds_dwordx4 v[200:201], off
	v_lshl_add_u64 v[200:201], s[10:11], 0, v[140:141]
	s_add_i32 m0, s42, 0xe000
	s_nop 0
	global_load_lds_dwordx4 v[200:201], off
	s_waitcnt vmcnt(8)
	s_waitcnt lgkmcnt(0)
	s_barrier
	s_waitcnt lgkmcnt(0)
	v_mfma_f32_16x16x32_bf16 v[124:127], v[146:149], v[196:199], v[124:127]
	v_mfma_f32_16x16x32_bf16 v[116:119], v[154:157], v[196:199], v[116:119]
	v_mfma_f32_16x16x32_bf16 v[108:111], v[146:149], v[208:211], v[108:111]
	v_mfma_f32_16x16x32_bf16 v[100:103], v[154:157], v[208:211], v[100:103]
	v_mfma_f32_16x16x32_bf16 v[92:95], v[146:149], v[216:219], v[92:95]
	v_mfma_f32_16x16x32_bf16 v[84:87], v[154:157], v[216:219], v[84:87]
	v_mfma_f32_16x16x32_bf16 v[76:79], v[146:149], v[224:227], v[76:79]
	v_mfma_f32_16x16x32_bf16 v[68:71], v[154:157], v[224:227], v[68:71]
	v_mfma_f32_16x16x32_bf16 v[124:127], v[150:153], v[204:207], v[124:127]
	v_mfma_f32_16x16x32_bf16 v[116:119], v[160:163], v[204:207], v[116:119]
	v_mfma_f32_16x16x32_bf16 v[108:111], v[150:153], v[212:215], v[108:111]
	v_mfma_f32_16x16x32_bf16 v[100:103], v[160:163], v[212:215], v[100:103]
	v_mfma_f32_16x16x32_bf16 v[92:95], v[150:153], v[220:223], v[92:95]
	v_mfma_f32_16x16x32_bf16 v[84:87], v[160:163], v[220:223], v[84:87]
	v_mfma_f32_16x16x32_bf16 v[76:79], v[150:153], v[228:231], v[76:79]
	v_mfma_f32_16x16x32_bf16 v[68:71], v[160:163], v[228:231], v[68:71]
	v_mfma_f32_16x16x32_bf16 v[120:123], v[180:183], v[196:199], v[120:123]
	v_mfma_f32_16x16x32_bf16 v[112:115], v[188:191], v[196:199], v[112:115]
	v_mfma_f32_16x16x32_bf16 v[104:107], v[180:183], v[208:211], v[104:107]
	v_mfma_f32_16x16x32_bf16 v[96:99], v[188:191], v[208:211], v[96:99]
	v_mfma_f32_16x16x32_bf16 v[88:91], v[180:183], v[216:219], v[88:91]
	v_mfma_f32_16x16x32_bf16 v[80:83], v[188:191], v[216:219], v[80:83]
	v_mfma_f32_16x16x32_bf16 v[72:75], v[180:183], v[224:227], v[72:75]
	v_mfma_f32_16x16x32_bf16 v[64:67], v[188:191], v[224:227], v[64:67]
	v_mfma_f32_16x16x32_bf16 v[120:123], v[184:187], v[204:207], v[120:123]
	v_mfma_f32_16x16x32_bf16 v[112:115], v[192:195], v[204:207], v[112:115]
	v_mfma_f32_16x16x32_bf16 v[104:107], v[184:187], v[212:215], v[104:107]
	v_mfma_f32_16x16x32_bf16 v[96:99], v[192:195], v[212:215], v[96:99]
	v_mfma_f32_16x16x32_bf16 v[88:91], v[184:187], v[220:223], v[88:91]
	v_mfma_f32_16x16x32_bf16 v[80:83], v[192:195], v[220:223], v[80:83]
	v_mfma_f32_16x16x32_bf16 v[72:75], v[184:187], v[228:231], v[72:75]
	v_mfma_f32_16x16x32_bf16 v[64:67], v[192:195], v[228:231], v[64:67]
	s_barrier
	s_add_i32 s57, s49, s23
	v_lshl_add_u64 v[200:201], s[4:5], 0, v[132:133]
	s_mov_b32 m0, s57
	ds_read_b128 v[196:199], v173 offset:16384
	ds_read_b128 v[204:207], v173 offset:17408
	ds_read_b128 v[208:211], v173 offset:18432
	ds_read_b128 v[212:215], v173 offset:19456
	ds_read_b128 v[216:219], v173 offset:20480
	ds_read_b128 v[220:223], v173 offset:21504
	ds_read_b128 v[224:227], v173 offset:22528
	ds_read_b128 v[228:231], v173 offset:23552
	global_load_lds_dwordx4 v[200:201], off
	s_add_i32 m0, s57, 0x2000
	s_add_u32 s58, s4, 0x40000
	v_lshl_add_u64 v[232:233], s[4:5], 0, v[128:129]
	s_addc_u32 s59, s5, 0
	s_add_i32 s57, s50, s23
	global_load_lds_dwordx4 v[232:233], off
	v_lshl_add_u64 v[234:235], s[58:59], 0, v[132:133]
	s_mov_b32 m0, s57
	v_lshl_add_u64 v[236:237], s[12:13], 0, v[130:131]
	global_load_lds_dwordx4 v[234:235], off
	v_lshl_add_u64 v[234:235], s[58:59], 0, v[128:129]
	s_add_i32 m0, s57, 0x2000
	s_nop 0
	global_load_lds_dwordx4 v[234:235], off
	v_lshl_add_u64 v[234:235], s[12:13], 0, v[134:135]
	s_mov_b32 m0, s42
	s_nop 0
	global_load_lds_dwordx4 v[234:235], off
	s_mov_b32 m0, s43
	s_nop 0
	global_load_lds_dwordx4 v[236:237], off
	s_waitcnt vmcnt(8)
	s_waitcnt lgkmcnt(0)
	s_barrier
	s_waitcnt lgkmcnt(0)
	v_mfma_f32_16x16x32_bf16 v[60:63], v[146:149], v[196:199], v[60:63]
	v_mfma_f32_16x16x32_bf16 v[52:55], v[154:157], v[196:199], v[52:55]
	v_mfma_f32_16x16x32_bf16 v[44:47], v[146:149], v[208:211], v[44:47]
	v_mfma_f32_16x16x32_bf16 v[36:39], v[154:157], v[208:211], v[36:39]
	v_mfma_f32_16x16x32_bf16 v[28:31], v[146:149], v[216:219], v[28:31]
	v_mfma_f32_16x16x32_bf16 v[20:23], v[154:157], v[216:219], v[20:23]
	v_mfma_f32_16x16x32_bf16 v[12:15], v[146:149], v[224:227], v[12:15]
	v_mfma_f32_16x16x32_bf16 v[4:7], v[154:157], v[224:227], v[4:7]
	v_mfma_f32_16x16x32_bf16 v[60:63], v[150:153], v[204:207], v[60:63]
	v_mfma_f32_16x16x32_bf16 v[52:55], v[160:163], v[204:207], v[52:55]
	v_mfma_f32_16x16x32_bf16 v[44:47], v[150:153], v[212:215], v[44:47]
	v_mfma_f32_16x16x32_bf16 v[36:39], v[160:163], v[212:215], v[36:39]
	v_mfma_f32_16x16x32_bf16 v[28:31], v[150:153], v[220:223], v[28:31]
	v_mfma_f32_16x16x32_bf16 v[20:23], v[160:163], v[220:223], v[20:23]
	v_mfma_f32_16x16x32_bf16 v[12:15], v[150:153], v[228:231], v[12:15]
	v_mfma_f32_16x16x32_bf16 v[4:7], v[160:163], v[228:231], v[4:7]
	v_mfma_f32_16x16x32_bf16 v[56:59], v[180:183], v[196:199], v[56:59]
	v_mfma_f32_16x16x32_bf16 v[48:51], v[188:191], v[196:199], v[48:51]
	v_mfma_f32_16x16x32_bf16 v[40:43], v[180:183], v[208:211], v[40:43]
	v_mfma_f32_16x16x32_bf16 v[32:35], v[188:191], v[208:211], v[32:35]
	v_mfma_f32_16x16x32_bf16 v[24:27], v[180:183], v[216:219], v[24:27]
	v_mfma_f32_16x16x32_bf16 v[16:19], v[188:191], v[216:219], v[16:19]
	v_mfma_f32_16x16x32_bf16 v[8:11], v[180:183], v[224:227], v[8:11]
	v_mfma_f32_16x16x32_bf16 v[0:3], v[188:191], v[224:227], v[0:3]
	v_mfma_f32_16x16x32_bf16 v[56:59], v[184:187], v[204:207], v[56:59]
	v_mfma_f32_16x16x32_bf16 v[48:51], v[192:195], v[204:207], v[48:51]
	v_mfma_f32_16x16x32_bf16 v[40:43], v[184:187], v[212:215], v[40:43]
	v_mfma_f32_16x16x32_bf16 v[32:35], v[192:195], v[212:215], v[32:35]
	v_mfma_f32_16x16x32_bf16 v[24:27], v[184:187], v[220:223], v[24:27]
	v_mfma_f32_16x16x32_bf16 v[16:19], v[192:195], v[220:223], v[16:19]
	v_mfma_f32_16x16x32_bf16 v[8:11], v[184:187], v[228:231], v[8:11]
	v_mfma_f32_16x16x32_bf16 v[0:3], v[192:195], v[228:231], v[0:3]
	s_barrier
	s_add_i32 s57, 0, 0x18000
	v_add_u32_e32 v158, s57, v165
	s_add_i32 s58, 0, 0x1c000
	ds_read_b128 v[146:149], v158
	ds_read_b128 v[150:153], v158 offset:1024
	ds_read_b128 v[154:157], v158 offset:2048
	ds_read_b128 v[160:163], v158 offset:3072
	v_add_u32_e32 v158, s58, v165
	ds_read_b128 v[180:183], v158
	ds_read_b128 v[184:187], v158 offset:1024
	ds_read_b128 v[188:191], v158 offset:2048
	ds_read_b128 v[192:195], v158 offset:3072
	s_add_u32 s12, s12, 0x40000
	s_addc_u32 s13, s13, 0
	s_mov_b32 m0, s44
	v_lshl_add_u64 v[238:239], s[12:13], 0, v[134:135]
	ds_read_b128 v[196:199], v173 offset:32768
	ds_read_b128 v[204:207], v173 offset:33792
	ds_read_b128 v[208:211], v173 offset:34816
	ds_read_b128 v[212:215], v173 offset:35840
	ds_read_b128 v[216:219], v173 offset:36864
	ds_read_b128 v[220:223], v173 offset:37888
	ds_read_b128 v[224:227], v173 offset:38912
	ds_read_b128 v[228:231], v173 offset:39936
	global_load_lds_dwordx4 v[238:239], off
	v_lshl_add_u64 v[238:239], s[12:13], 0, v[130:131]
	s_mov_b32 m0, s45
	s_nop 0
	global_load_lds_dwordx4 v[238:239], off
	s_waitcnt vmcnt(8)
	s_waitcnt lgkmcnt(0)
	s_barrier
	s_waitcnt lgkmcnt(0)
	v_mfma_f32_16x16x32_bf16 v[124:127], v[146:149], v[196:199], v[124:127]
	v_mfma_f32_16x16x32_bf16 v[116:119], v[154:157], v[196:199], v[116:119]
	v_mfma_f32_16x16x32_bf16 v[108:111], v[146:149], v[208:211], v[108:111]
	v_mfma_f32_16x16x32_bf16 v[100:103], v[154:157], v[208:211], v[100:103]
	v_mfma_f32_16x16x32_bf16 v[92:95], v[146:149], v[216:219], v[92:95]
	v_mfma_f32_16x16x32_bf16 v[84:87], v[154:157], v[216:219], v[84:87]
	v_mfma_f32_16x16x32_bf16 v[76:79], v[146:149], v[224:227], v[76:79]
	v_mfma_f32_16x16x32_bf16 v[68:71], v[154:157], v[224:227], v[68:71]
	v_mfma_f32_16x16x32_bf16 v[124:127], v[150:153], v[204:207], v[124:127]
	v_mfma_f32_16x16x32_bf16 v[116:119], v[160:163], v[204:207], v[116:119]
	v_mfma_f32_16x16x32_bf16 v[108:111], v[150:153], v[212:215], v[108:111]
	v_mfma_f32_16x16x32_bf16 v[100:103], v[160:163], v[212:215], v[100:103]
	v_mfma_f32_16x16x32_bf16 v[92:95], v[150:153], v[220:223], v[92:95]
	v_mfma_f32_16x16x32_bf16 v[84:87], v[160:163], v[220:223], v[84:87]
	v_mfma_f32_16x16x32_bf16 v[76:79], v[150:153], v[228:231], v[76:79]
	v_mfma_f32_16x16x32_bf16 v[68:71], v[160:163], v[228:231], v[68:71]
	v_mfma_f32_16x16x32_bf16 v[120:123], v[180:183], v[196:199], v[120:123]
	v_mfma_f32_16x16x32_bf16 v[112:115], v[188:191], v[196:199], v[112:115]
	v_mfma_f32_16x16x32_bf16 v[104:107], v[180:183], v[208:211], v[104:107]
	v_mfma_f32_16x16x32_bf16 v[96:99], v[188:191], v[208:211], v[96:99]
	v_mfma_f32_16x16x32_bf16 v[88:91], v[180:183], v[216:219], v[88:91]
	v_mfma_f32_16x16x32_bf16 v[80:83], v[188:191], v[216:219], v[80:83]
	v_mfma_f32_16x16x32_bf16 v[72:75], v[180:183], v[224:227], v[72:75]
	v_mfma_f32_16x16x32_bf16 v[64:67], v[188:191], v[224:227], v[64:67]
	v_mfma_f32_16x16x32_bf16 v[120:123], v[184:187], v[204:207], v[120:123]
	v_mfma_f32_16x16x32_bf16 v[112:115], v[192:195], v[204:207], v[112:115]
	v_mfma_f32_16x16x32_bf16 v[104:107], v[184:187], v[212:215], v[104:107]
	v_mfma_f32_16x16x32_bf16 v[96:99], v[192:195], v[212:215], v[96:99]
	v_mfma_f32_16x16x32_bf16 v[88:91], v[184:187], v[220:223], v[88:91]
	v_mfma_f32_16x16x32_bf16 v[80:83], v[192:195], v[220:223], v[80:83]
	v_mfma_f32_16x16x32_bf16 v[72:75], v[184:187], v[228:231], v[72:75]
	v_mfma_f32_16x16x32_bf16 v[64:67], v[192:195], v[228:231], v[64:67]
	s_barrier
	s_add_i32 s12, s57, s23
	v_lshl_add_u64 v[200:201], v[200:201], 0, s[28:29]
	s_mov_b32 m0, s12
	ds_read_b128 v[196:199], v173 offset:49152
	ds_read_b128 v[204:207], v173 offset:50176
	ds_read_b128 v[208:211], v173 offset:51200
	ds_read_b128 v[212:215], v173 offset:52224
	ds_read_b128 v[216:219], v173 offset:53248
	ds_read_b128 v[220:223], v173 offset:54272
	ds_read_b128 v[224:227], v173 offset:55296
	ds_read_b128 v[228:231], v173 offset:56320
	global_load_lds_dwordx4 v[200:201], off
	s_add_i32 m0, s12, 0x2000
	s_add_u32 s4, s4, 0x40080
	v_lshl_add_u64 v[200:201], v[232:233], 0, s[28:29]
	s_addc_u32 s5, s5, 0
	s_add_i32 s12, s58, s23
	global_load_lds_dwordx4 v[200:201], off
	v_lshl_add_u64 v[200:201], s[4:5], 0, v[132:133]
	s_mov_b32 m0, s12
	s_nop 0
	global_load_lds_dwordx4 v[200:201], off
	v_lshl_add_u64 v[200:201], s[4:5], 0, v[128:129]
	s_add_i32 m0, s12, 0x2000
	s_nop 0
	global_load_lds_dwordx4 v[200:201], off
	v_lshl_add_u64 v[200:201], v[234:235], 0, s[28:29]
	s_mov_b32 m0, s47
	s_nop 0
	global_load_lds_dwordx4 v[200:201], off
	v_lshl_add_u64 v[200:201], v[236:237], 0, s[28:29]
	s_mov_b32 m0, s48
	s_nop 0
	global_load_lds_dwordx4 v[200:201], off
	s_waitcnt vmcnt(8)
	s_waitcnt lgkmcnt(0)
	s_barrier
	s_waitcnt lgkmcnt(0)
	v_mfma_f32_16x16x32_bf16 v[60:63], v[146:149], v[196:199], v[60:63]
	v_mfma_f32_16x16x32_bf16 v[52:55], v[154:157], v[196:199], v[52:55]
	v_mfma_f32_16x16x32_bf16 v[44:47], v[146:149], v[208:211], v[44:47]
	v_mfma_f32_16x16x32_bf16 v[36:39], v[154:157], v[208:211], v[36:39]
	v_mfma_f32_16x16x32_bf16 v[28:31], v[146:149], v[216:219], v[28:31]
	v_mfma_f32_16x16x32_bf16 v[20:23], v[154:157], v[216:219], v[20:23]
	v_mfma_f32_16x16x32_bf16 v[12:15], v[146:149], v[224:227], v[12:15]
	v_mfma_f32_16x16x32_bf16 v[4:7], v[154:157], v[224:227], v[4:7]
	v_mfma_f32_16x16x32_bf16 v[60:63], v[150:153], v[204:207], v[60:63]
	v_mfma_f32_16x16x32_bf16 v[52:55], v[160:163], v[204:207], v[52:55]
	v_mfma_f32_16x16x32_bf16 v[44:47], v[150:153], v[212:215], v[44:47]
	v_mfma_f32_16x16x32_bf16 v[36:39], v[160:163], v[212:215], v[36:39]
	v_mfma_f32_16x16x32_bf16 v[28:31], v[150:153], v[220:223], v[28:31]
	v_mfma_f32_16x16x32_bf16 v[20:23], v[160:163], v[220:223], v[20:23]
	v_mfma_f32_16x16x32_bf16 v[12:15], v[150:153], v[228:231], v[12:15]
	v_mfma_f32_16x16x32_bf16 v[4:7], v[160:163], v[228:231], v[4:7]
	v_mfma_f32_16x16x32_bf16 v[56:59], v[180:183], v[196:199], v[56:59]
	v_mfma_f32_16x16x32_bf16 v[48:51], v[188:191], v[196:199], v[48:51]
	v_mfma_f32_16x16x32_bf16 v[40:43], v[180:183], v[208:211], v[40:43]
	v_mfma_f32_16x16x32_bf16 v[32:35], v[188:191], v[208:211], v[32:35]
	v_mfma_f32_16x16x32_bf16 v[24:27], v[180:183], v[216:219], v[24:27]
	v_mfma_f32_16x16x32_bf16 v[16:19], v[188:191], v[216:219], v[16:19]
	v_mfma_f32_16x16x32_bf16 v[8:11], v[180:183], v[224:227], v[8:11]
	v_mfma_f32_16x16x32_bf16 v[0:3], v[188:191], v[224:227], v[0:3]
	v_mfma_f32_16x16x32_bf16 v[56:59], v[184:187], v[204:207], v[56:59]
	v_mfma_f32_16x16x32_bf16 v[48:51], v[192:195], v[204:207], v[48:51]
	v_mfma_f32_16x16x32_bf16 v[40:43], v[184:187], v[212:215], v[40:43]
	v_mfma_f32_16x16x32_bf16 v[32:35], v[192:195], v[212:215], v[32:35]
	v_mfma_f32_16x16x32_bf16 v[24:27], v[184:187], v[220:223], v[24:27]
	v_mfma_f32_16x16x32_bf16 v[16:19], v[192:195], v[220:223], v[16:19]
	v_mfma_f32_16x16x32_bf16 v[8:11], v[184:187], v[228:231], v[8:11]
	v_mfma_f32_16x16x32_bf16 v[0:3], v[192:195], v[228:231], v[0:3]
	s_barrier
	s_add_i32 s56, s56, 2
	s_add_u32 s10, s10, 0x100
	s_addc_u32 s11, s11, 0
	s_add_u32 s54, s54, 0x100
	s_addc_u32 s55, s55, 0
	s_cmp_gt_u32 s56, 13
	s_cbranch_scc0 .LBB0_483
	s_and_b64 vcc, exec, s[30:31]
	s_cbranch_vccz .LBB0_486
	s_barrier

.LBB0_559:
	ds_read_b128 v[128:131], v189
	ds_read_b128 v[132:135], v189 offset:1024
	ds_read_b128 v[136:139], v189 offset:2048
	ds_read_b128 v[140:143], v189 offset:3072
	ds_read_b128 v[144:147], v190
	ds_read_b128 v[148:151], v190 offset:1024
	ds_read_b128 v[168:171], v190 offset:2048
	ds_read_b128 v[172:175], v190 offset:3072
	s_add_u32 s4, s22, 0x100
	s_addc_u32 s5, s23, 0
	s_cmp_eq_u32 s57, 40
	s_cselect_b32 s41, s11, s5
	s_cselect_b32 s40, s10, s4
	s_cselect_b32 s39, s37, s56
	s_cselect_b32 s38, s36, s55
	v_lshl_add_u64 v[184:185], s[22:23], 0, v[160:161]
	s_add_i32 m0, s43, 0xc000
	ds_read_b128 v[176:179], v191
	ds_read_b128 v[180:183], v191 offset:1024
	ds_read_b128 v[194:197], v191 offset:2048
	ds_read_b128 v[198:201], v191 offset:3072
	ds_read_b128 v[204:207], v191 offset:4096
	ds_read_b128 v[208:211], v191 offset:5120
	ds_read_b128 v[212:215], v191 offset:6144
	ds_read_b128 v[216:219], v191 offset:7168
	global_load_lds_dwordx4 v[184:185], off
	v_lshl_add_u64 v[184:185], s[22:23], 0, v[162:163]
	s_add_i32 m0, s43, 0xe000
	s_nop 0
	global_load_lds_dwordx4 v[184:185], off
	s_waitcnt vmcnt(8)
	s_waitcnt lgkmcnt(0)
	s_barrier
	s_waitcnt lgkmcnt(0)
	v_mfma_f32_16x16x32_bf16 v[124:127], v[128:131], v[176:179], v[124:127]
	v_mfma_f32_16x16x32_bf16 v[120:123], v[136:139], v[176:179], v[120:123]
	v_mfma_f32_16x16x32_bf16 v[108:111], v[128:131], v[194:197], v[108:111]
	v_mfma_f32_16x16x32_bf16 v[104:107], v[136:139], v[194:197], v[104:107]
	v_mfma_f32_16x16x32_bf16 v[92:95], v[128:131], v[204:207], v[92:95]
	v_mfma_f32_16x16x32_bf16 v[88:91], v[136:139], v[204:207], v[88:91]
	v_mfma_f32_16x16x32_bf16 v[76:79], v[128:131], v[212:215], v[76:79]
	v_mfma_f32_16x16x32_bf16 v[72:75], v[136:139], v[212:215], v[72:75]
	v_mfma_f32_16x16x32_bf16 v[124:127], v[132:135], v[180:183], v[124:127]
	v_mfma_f32_16x16x32_bf16 v[120:123], v[140:143], v[180:183], v[120:123]
	v_mfma_f32_16x16x32_bf16 v[108:111], v[132:135], v[198:201], v[108:111]
	v_mfma_f32_16x16x32_bf16 v[104:107], v[140:143], v[198:201], v[104:107]
	v_mfma_f32_16x16x32_bf16 v[92:95], v[132:135], v[208:211], v[92:95]
	v_mfma_f32_16x16x32_bf16 v[88:91], v[140:143], v[208:211], v[88:91]
	v_mfma_f32_16x16x32_bf16 v[76:79], v[132:135], v[216:219], v[76:79]
	v_mfma_f32_16x16x32_bf16 v[72:75], v[140:143], v[216:219], v[72:75]
	v_mfma_f32_16x16x32_bf16 v[116:119], v[144:147], v[176:179], v[116:119]
	v_mfma_f32_16x16x32_bf16 v[112:115], v[168:171], v[176:179], v[112:115]
	v_mfma_f32_16x16x32_bf16 v[100:103], v[144:147], v[194:197], v[100:103]
	v_mfma_f32_16x16x32_bf16 v[96:99], v[168:171], v[194:197], v[96:99]
	v_mfma_f32_16x16x32_bf16 v[84:87], v[144:147], v[204:207], v[84:87]
	v_mfma_f32_16x16x32_bf16 v[80:83], v[168:171], v[204:207], v[80:83]
	v_mfma_f32_16x16x32_bf16 v[68:71], v[144:147], v[212:215], v[68:71]
	v_mfma_f32_16x16x32_bf16 v[64:67], v[168:171], v[212:215], v[64:67]
	v_mfma_f32_16x16x32_bf16 v[116:119], v[148:151], v[180:183], v[116:119]
	v_mfma_f32_16x16x32_bf16 v[112:115], v[172:175], v[180:183], v[112:115]
	v_mfma_f32_16x16x32_bf16 v[100:103], v[148:151], v[198:201], v[100:103]
	v_mfma_f32_16x16x32_bf16 v[96:99], v[172:175], v[198:201], v[96:99]
	v_mfma_f32_16x16x32_bf16 v[84:87], v[148:151], v[208:211], v[84:87]
	v_mfma_f32_16x16x32_bf16 v[80:83], v[172:175], v[208:211], v[80:83]
	v_mfma_f32_16x16x32_bf16 v[68:71], v[148:151], v[216:219], v[68:71]
	v_mfma_f32_16x16x32_bf16 v[64:67], v[172:175], v[216:219], v[64:67]
	s_barrier
	s_add_i32 s22, s49, s42
	v_lshl_add_u64 v[184:185], s[38:39], 0, v[154:155]
	s_mov_b32 m0, s22
	ds_read_b128 v[176:179], v191 offset:16384
	ds_read_b128 v[180:183], v191 offset:17408
	ds_read_b128 v[194:197], v191 offset:18432
	ds_read_b128 v[198:201], v191 offset:19456
	ds_read_b128 v[204:207], v191 offset:20480
	ds_read_b128 v[208:211], v191 offset:21504
	ds_read_b128 v[212:215], v191 offset:22528
	ds_read_b128 v[216:219], v191 offset:23552
	global_load_lds_dwordx4 v[184:185], off
	s_add_i32 m0, s22, 0x2000
	s_add_u32 s22, s38, 0xb0000
	v_lshl_add_u64 v[220:221], s[38:39], 0, v[158:159]
	s_addc_u32 s23, s39, 0
	s_add_i32 s58, s50, s42
	global_load_lds_dwordx4 v[220:221], off
	v_lshl_add_u64 v[222:223], s[22:23], 0, v[154:155]
	s_mov_b32 m0, s58
	v_lshl_add_u64 v[224:225], s[40:41], 0, v[156:157]
	global_load_lds_dwordx4 v[222:223], off
	v_lshl_add_u64 v[222:223], s[22:23], 0, v[158:159]
	s_add_i32 m0, s58, 0x2000
	s_nop 0
	global_load_lds_dwordx4 v[222:223], off
	v_lshl_add_u64 v[222:223], s[40:41], 0, v[152:153]
	s_mov_b32 m0, s43
	s_nop 0
	global_load_lds_dwordx4 v[222:223], off
	s_mov_b32 m0, s44
	s_nop 0
	global_load_lds_dwordx4 v[224:225], off
	s_waitcnt vmcnt(8)
	s_waitcnt lgkmcnt(0)
	s_barrier
	s_waitcnt lgkmcnt(0)
	v_mfma_f32_16x16x32_bf16 v[60:63], v[128:131], v[176:179], v[60:63]
	v_mfma_f32_16x16x32_bf16 v[56:59], v[136:139], v[176:179], v[56:59]
	v_mfma_f32_16x16x32_bf16 v[44:47], v[128:131], v[194:197], v[44:47]
	v_mfma_f32_16x16x32_bf16 v[40:43], v[136:139], v[194:197], v[40:43]
	v_mfma_f32_16x16x32_bf16 v[28:31], v[128:131], v[204:207], v[28:31]
	v_mfma_f32_16x16x32_bf16 v[24:27], v[136:139], v[204:207], v[24:27]
	v_mfma_f32_16x16x32_bf16 v[12:15], v[128:131], v[212:215], v[12:15]
	v_mfma_f32_16x16x32_bf16 v[8:11], v[136:139], v[212:215], v[8:11]
	v_mfma_f32_16x16x32_bf16 v[60:63], v[132:135], v[180:183], v[60:63]
	v_mfma_f32_16x16x32_bf16 v[56:59], v[140:143], v[180:183], v[56:59]
	v_mfma_f32_16x16x32_bf16 v[44:47], v[132:135], v[198:201], v[44:47]
	v_mfma_f32_16x16x32_bf16 v[40:43], v[140:143], v[198:201], v[40:43]
	v_mfma_f32_16x16x32_bf16 v[28:31], v[132:135], v[208:211], v[28:31]
	v_mfma_f32_16x16x32_bf16 v[24:27], v[140:143], v[208:211], v[24:27]
	v_mfma_f32_16x16x32_bf16 v[12:15], v[132:135], v[216:219], v[12:15]
	v_mfma_f32_16x16x32_bf16 v[8:11], v[140:143], v[216:219], v[8:11]
	v_mfma_f32_16x16x32_bf16 v[52:55], v[144:147], v[176:179], v[52:55]
	v_mfma_f32_16x16x32_bf16 v[48:51], v[168:171], v[176:179], v[48:51]
	v_mfma_f32_16x16x32_bf16 v[36:39], v[144:147], v[194:197], v[36:39]
	v_mfma_f32_16x16x32_bf16 v[32:35], v[168:171], v[194:197], v[32:35]
	v_mfma_f32_16x16x32_bf16 v[20:23], v[144:147], v[204:207], v[20:23]
	v_mfma_f32_16x16x32_bf16 v[16:19], v[168:171], v[204:207], v[16:19]
	v_mfma_f32_16x16x32_bf16 v[4:7], v[144:147], v[212:215], v[4:7]
	v_mfma_f32_16x16x32_bf16 v[0:3], v[168:171], v[212:215], v[0:3]
	v_mfma_f32_16x16x32_bf16 v[52:55], v[148:151], v[180:183], v[52:55]
	v_mfma_f32_16x16x32_bf16 v[48:51], v[172:175], v[180:183], v[48:51]
	v_mfma_f32_16x16x32_bf16 v[36:39], v[148:151], v[198:201], v[36:39]
	v_mfma_f32_16x16x32_bf16 v[32:35], v[172:175], v[198:201], v[32:35]
	v_mfma_f32_16x16x32_bf16 v[20:23], v[148:151], v[208:211], v[20:23]
	v_mfma_f32_16x16x32_bf16 v[16:19], v[172:175], v[208:211], v[16:19]
	v_mfma_f32_16x16x32_bf16 v[4:7], v[148:151], v[216:219], v[4:7]
	v_mfma_f32_16x16x32_bf16 v[0:3], v[172:175], v[216:219], v[0:3]
	s_barrier
	s_add_i32 s58, 0, 0x18000
	s_add_i32 s59, 0, 0x1c000
	v_add_u32_e32 v140, s58, v187
	v_add_u32_e32 v172, s59, v187
	ds_read_b128 v[128:131], v140
	ds_read_b128 v[132:135], v140 offset:1024
	ds_read_b128 v[136:139], v140 offset:2048
	ds_read_b128 v[140:143], v140 offset:3072
	ds_read_b128 v[144:147], v172
	ds_read_b128 v[148:151], v172 offset:1024
	ds_read_b128 v[168:171], v172 offset:2048
	ds_read_b128 v[172:175], v172 offset:3072
	s_add_u32 s22, s40, 0xb0000
	s_addc_u32 s23, s41, 0
	s_mov_b32 m0, s45
	v_lshl_add_u64 v[226:227], s[22:23], 0, v[152:153]
	ds_read_b128 v[176:179], v191 offset:32768
	ds_read_b128 v[180:183], v191 offset:33792
	ds_read_b128 v[194:197], v191 offset:34816
	ds_read_b128 v[198:201], v191 offset:35840
	ds_read_b128 v[204:207], v191 offset:36864
	ds_read_b128 v[208:211], v191 offset:37888
	ds_read_b128 v[212:215], v191 offset:38912
	ds_read_b128 v[216:219], v191 offset:39936
	global_load_lds_dwordx4 v[226:227], off
	v_lshl_add_u64 v[226:227], s[22:23], 0, v[156:157]
	s_mov_b32 m0, s46
	s_nop 0
	global_load_lds_dwordx4 v[226:227], off
	s_waitcnt vmcnt(8)
	s_waitcnt lgkmcnt(0)
	s_barrier
	s_waitcnt lgkmcnt(0)
	v_mfma_f32_16x16x32_bf16 v[124:127], v[128:131], v[176:179], v[124:127]
	v_mfma_f32_16x16x32_bf16 v[120:123], v[136:139], v[176:179], v[120:123]
	v_mfma_f32_16x16x32_bf16 v[108:111], v[128:131], v[194:197], v[108:111]
	v_mfma_f32_16x16x32_bf16 v[104:107], v[136:139], v[194:197], v[104:107]
	v_mfma_f32_16x16x32_bf16 v[92:95], v[128:131], v[204:207], v[92:95]
	v_mfma_f32_16x16x32_bf16 v[88:91], v[136:139], v[204:207], v[88:91]
	v_mfma_f32_16x16x32_bf16 v[76:79], v[128:131], v[212:215], v[76:79]
	v_mfma_f32_16x16x32_bf16 v[72:75], v[136:139], v[212:215], v[72:75]
	v_mfma_f32_16x16x32_bf16 v[124:127], v[132:135], v[180:183], v[124:127]
	v_mfma_f32_16x16x32_bf16 v[120:123], v[140:143], v[180:183], v[120:123]
	v_mfma_f32_16x16x32_bf16 v[108:111], v[132:135], v[198:201], v[108:111]
	v_mfma_f32_16x16x32_bf16 v[104:107], v[140:143], v[198:201], v[104:107]
	v_mfma_f32_16x16x32_bf16 v[92:95], v[132:135], v[208:211], v[92:95]
	v_mfma_f32_16x16x32_bf16 v[88:91], v[140:143], v[208:211], v[88:91]
	v_mfma_f32_16x16x32_bf16 v[76:79], v[132:135], v[216:219], v[76:79]
	v_mfma_f32_16x16x32_bf16 v[72:75], v[140:143], v[216:219], v[72:75]
	v_mfma_f32_16x16x32_bf16 v[116:119], v[144:147], v[176:179], v[116:119]
	v_mfma_f32_16x16x32_bf16 v[112:115], v[168:171], v[176:179], v[112:115]
	v_mfma_f32_16x16x32_bf16 v[100:103], v[144:147], v[194:197], v[100:103]
	v_mfma_f32_16x16x32_bf16 v[96:99], v[168:171], v[194:197], v[96:99]
	v_mfma_f32_16x16x32_bf16 v[84:87], v[144:147], v[204:207], v[84:87]
	v_mfma_f32_16x16x32_bf16 v[80:83], v[168:171], v[204:207], v[80:83]
	v_mfma_f32_16x16x32_bf16 v[68:71], v[144:147], v[212:215], v[68:71]
	v_mfma_f32_16x16x32_bf16 v[64:67], v[168:171], v[212:215], v[64:67]
	v_mfma_f32_16x16x32_bf16 v[116:119], v[148:151], v[180:183], v[116:119]
	v_mfma_f32_16x16x32_bf16 v[112:115], v[172:175], v[180:183], v[112:115]
	v_mfma_f32_16x16x32_bf16 v[100:103], v[148:151], v[198:201], v[100:103]
	v_mfma_f32_16x16x32_bf16 v[96:99], v[172:175], v[198:201], v[96:99]
	v_mfma_f32_16x16x32_bf16 v[84:87], v[148:151], v[208:211], v[84:87]
	v_mfma_f32_16x16x32_bf16 v[80:83], v[172:175], v[208:211], v[80:83]
	v_mfma_f32_16x16x32_bf16 v[68:71], v[148:151], v[216:219], v[68:71]
	v_mfma_f32_16x16x32_bf16 v[64:67], v[172:175], v[216:219], v[64:67]
	s_barrier
	s_add_i32 s22, s58, s42
	v_lshl_add_u64 v[184:185], v[184:185], 0, s[30:31]
	s_mov_b32 m0, s22
	ds_read_b128 v[176:179], v191 offset:49152
	ds_read_b128 v[180:183], v191 offset:50176
	ds_read_b128 v[194:197], v191 offset:51200
	ds_read_b128 v[198:201], v191 offset:52224
	ds_read_b128 v[204:207], v191 offset:53248
	ds_read_b128 v[208:211], v191 offset:54272
	ds_read_b128 v[212:215], v191 offset:55296
	ds_read_b128 v[216:219], v191 offset:56320
	global_load_lds_dwordx4 v[184:185], off
	s_add_i32 m0, s22, 0x2000
	s_add_u32 s22, s38, 0xb0080
	v_lshl_add_u64 v[184:185], v[220:221], 0, s[30:31]
	s_addc_u32 s23, s39, 0
	s_add_i32 s38, s59, s42
	global_load_lds_dwordx4 v[184:185], off
	v_lshl_add_u64 v[184:185], s[22:23], 0, v[154:155]
	s_mov_b32 m0, s38
	s_nop 0
	global_load_lds_dwordx4 v[184:185], off
	v_lshl_add_u64 v[184:185], s[22:23], 0, v[158:159]
	s_add_i32 m0, s38, 0x2000
	s_nop 0
	global_load_lds_dwordx4 v[184:185], off
	v_lshl_add_u64 v[184:185], v[222:223], 0, s[30:31]
	s_mov_b32 m0, s33
	s_nop 0
	global_load_lds_dwordx4 v[184:185], off
	v_lshl_add_u64 v[184:185], v[224:225], 0, s[30:31]
	s_mov_b32 m0, s48
	s_nop 0
	global_load_lds_dwordx4 v[184:185], off
	s_waitcnt vmcnt(8)
	s_waitcnt lgkmcnt(0)
	s_barrier
	s_waitcnt lgkmcnt(0)
	v_mfma_f32_16x16x32_bf16 v[60:63], v[128:131], v[176:179], v[60:63]
	v_mfma_f32_16x16x32_bf16 v[56:59], v[136:139], v[176:179], v[56:59]
	v_mfma_f32_16x16x32_bf16 v[44:47], v[128:131], v[194:197], v[44:47]
	v_mfma_f32_16x16x32_bf16 v[40:43], v[136:139], v[194:197], v[40:43]
	v_mfma_f32_16x16x32_bf16 v[28:31], v[128:131], v[204:207], v[28:31]
	v_mfma_f32_16x16x32_bf16 v[24:27], v[136:139], v[204:207], v[24:27]
	v_mfma_f32_16x16x32_bf16 v[12:15], v[128:131], v[212:215], v[12:15]
	v_mfma_f32_16x16x32_bf16 v[8:11], v[136:139], v[212:215], v[8:11]
	v_mfma_f32_16x16x32_bf16 v[60:63], v[132:135], v[180:183], v[60:63]
	v_mfma_f32_16x16x32_bf16 v[56:59], v[140:143], v[180:183], v[56:59]
	v_mfma_f32_16x16x32_bf16 v[44:47], v[132:135], v[198:201], v[44:47]
	v_mfma_f32_16x16x32_bf16 v[40:43], v[140:143], v[198:201], v[40:43]
	v_mfma_f32_16x16x32_bf16 v[28:31], v[132:135], v[208:211], v[28:31]
	v_mfma_f32_16x16x32_bf16 v[24:27], v[140:143], v[208:211], v[24:27]
	v_mfma_f32_16x16x32_bf16 v[12:15], v[132:135], v[216:219], v[12:15]
	v_mfma_f32_16x16x32_bf16 v[8:11], v[140:143], v[216:219], v[8:11]
	v_mfma_f32_16x16x32_bf16 v[52:55], v[144:147], v[176:179], v[52:55]
	v_mfma_f32_16x16x32_bf16 v[48:51], v[168:171], v[176:179], v[48:51]
	v_mfma_f32_16x16x32_bf16 v[36:39], v[144:147], v[194:197], v[36:39]
	v_mfma_f32_16x16x32_bf16 v[32:35], v[168:171], v[194:197], v[32:35]
	v_mfma_f32_16x16x32_bf16 v[20:23], v[144:147], v[204:207], v[20:23]
	v_mfma_f32_16x16x32_bf16 v[16:19], v[168:171], v[204:207], v[16:19]
	v_mfma_f32_16x16x32_bf16 v[4:7], v[144:147], v[212:215], v[4:7]
	v_mfma_f32_16x16x32_bf16 v[0:3], v[168:171], v[212:215], v[0:3]
	v_mfma_f32_16x16x32_bf16 v[52:55], v[148:151], v[180:183], v[52:55]
	v_mfma_f32_16x16x32_bf16 v[48:51], v[172:175], v[180:183], v[48:51]
	v_mfma_f32_16x16x32_bf16 v[36:39], v[148:151], v[198:201], v[36:39]
	v_mfma_f32_16x16x32_bf16 v[32:35], v[172:175], v[198:201], v[32:35]
	v_mfma_f32_16x16x32_bf16 v[20:23], v[148:151], v[208:211], v[20:23]
	v_mfma_f32_16x16x32_bf16 v[16:19], v[172:175], v[208:211], v[16:19]
	v_mfma_f32_16x16x32_bf16 v[4:7], v[148:151], v[216:219], v[4:7]
	v_mfma_f32_16x16x32_bf16 v[0:3], v[172:175], v[216:219], v[0:3]
	s_barrier
	s_add_i32 s57, s57, 2
	s_add_u32 s55, s55, 0x100
	s_addc_u32 s56, s56, 0
	s_cmp_gt_u32 s57, 41
	s_mov_b64 s[22:23], s[4:5]
	s_cbranch_scc0 .LBB0_559
	s_and_b64 vcc, exec, s[34:35]
	s_cbranch_vccz .LBB0_562
	s_barrier

.LBB0_643:
	ds_read_b128 v[128:131], v191
	ds_read_b128 v[132:135], v191 offset:1024
	ds_read_b128 v[156:159], v191 offset:2048
	ds_read_b128 v[160:163], v191 offset:3072
	ds_read_b128 v[164:167], v192
	ds_read_b128 v[168:171], v192 offset:1024
	ds_read_b128 v[172:175], v192 offset:2048
	ds_read_b128 v[176:179], v192 offset:3072
	s_add_u32 s4, s22, 0xfffc0080
	s_addc_u32 s5, s23, -1
	s_cmp_eq_u32 s63, 12
	s_cselect_b32 s47, s13, s5
	s_cselect_b32 s46, s17, s4
	s_cselect_b32 s5, s33, s62
	s_cselect_b32 s4, s39, s41
	v_lshl_add_u64 v[224:225], s[22:23], 0, v[148:149]
	s_add_i32 m0, s49, 0xc000
	ds_read_b128 v[180:183], v193
	ds_read_b128 v[184:187], v193 offset:1024
	ds_read_b128 v[198:201], v193 offset:2048
	ds_read_b128 v[204:207], v193 offset:3072
	ds_read_b128 v[208:211], v193 offset:4096
	ds_read_b128 v[212:215], v193 offset:5120
	ds_read_b128 v[216:219], v193 offset:6144
	ds_read_b128 v[220:223], v193 offset:7168
	global_load_lds_dwordx4 v[224:225], off
	v_lshl_add_u64 v[224:225], s[22:23], 0, v[150:151]
	s_add_i32 m0, s49, 0xe000
	s_nop 0
	global_load_lds_dwordx4 v[224:225], off
	s_waitcnt vmcnt(8)
	s_waitcnt lgkmcnt(0)
	s_barrier
	s_waitcnt lgkmcnt(0)
	v_mfma_f32_16x16x32_bf16 v[124:127], v[128:131], v[180:183], v[124:127]
	v_mfma_f32_16x16x32_bf16 v[120:123], v[156:159], v[180:183], v[120:123]
	v_mfma_f32_16x16x32_bf16 v[108:111], v[128:131], v[198:201], v[108:111]
	v_mfma_f32_16x16x32_bf16 v[104:107], v[156:159], v[198:201], v[104:107]
	v_mfma_f32_16x16x32_bf16 v[92:95], v[128:131], v[208:211], v[92:95]
	v_mfma_f32_16x16x32_bf16 v[88:91], v[156:159], v[208:211], v[88:91]
	v_mfma_f32_16x16x32_bf16 v[76:79], v[128:131], v[216:219], v[76:79]
	v_mfma_f32_16x16x32_bf16 v[72:75], v[156:159], v[216:219], v[72:75]
	v_mfma_f32_16x16x32_bf16 v[124:127], v[132:135], v[184:187], v[124:127]
	v_mfma_f32_16x16x32_bf16 v[120:123], v[160:163], v[184:187], v[120:123]
	v_mfma_f32_16x16x32_bf16 v[108:111], v[132:135], v[204:207], v[108:111]
	v_mfma_f32_16x16x32_bf16 v[104:107], v[160:163], v[204:207], v[104:107]
	v_mfma_f32_16x16x32_bf16 v[92:95], v[132:135], v[212:215], v[92:95]
	v_mfma_f32_16x16x32_bf16 v[88:91], v[160:163], v[212:215], v[88:91]
	v_mfma_f32_16x16x32_bf16 v[76:79], v[132:135], v[220:223], v[76:79]
	v_mfma_f32_16x16x32_bf16 v[72:75], v[160:163], v[220:223], v[72:75]
	v_mfma_f32_16x16x32_bf16 v[116:119], v[164:167], v[180:183], v[116:119]
	v_mfma_f32_16x16x32_bf16 v[112:115], v[172:175], v[180:183], v[112:115]
	v_mfma_f32_16x16x32_bf16 v[100:103], v[164:167], v[198:201], v[100:103]
	v_mfma_f32_16x16x32_bf16 v[96:99], v[172:175], v[198:201], v[96:99]
	v_mfma_f32_16x16x32_bf16 v[84:87], v[164:167], v[208:211], v[84:87]
	v_mfma_f32_16x16x32_bf16 v[80:83], v[172:175], v[208:211], v[80:83]
	v_mfma_f32_16x16x32_bf16 v[68:71], v[164:167], v[216:219], v[68:71]
	v_mfma_f32_16x16x32_bf16 v[64:67], v[172:175], v[216:219], v[64:67]
	v_mfma_f32_16x16x32_bf16 v[116:119], v[168:171], v[184:187], v[116:119]
	v_mfma_f32_16x16x32_bf16 v[112:115], v[176:179], v[184:187], v[112:115]
	v_mfma_f32_16x16x32_bf16 v[100:103], v[168:171], v[204:207], v[100:103]
	v_mfma_f32_16x16x32_bf16 v[96:99], v[176:179], v[204:207], v[96:99]
	v_mfma_f32_16x16x32_bf16 v[84:87], v[168:171], v[212:215], v[84:87]
	v_mfma_f32_16x16x32_bf16 v[80:83], v[176:179], v[212:215], v[80:83]
	v_mfma_f32_16x16x32_bf16 v[68:71], v[168:171], v[220:223], v[68:71]
	v_mfma_f32_16x16x32_bf16 v[64:67], v[176:179], v[220:223], v[64:67]
	s_barrier
	s_add_i32 s64, s59, s48
	v_lshl_add_u64 v[224:225], s[4:5], 0, v[138:139]
	s_mov_b32 m0, s64
	ds_read_b128 v[180:183], v193 offset:16384
	ds_read_b128 v[184:187], v193 offset:17408
	ds_read_b128 v[198:201], v193 offset:18432
	ds_read_b128 v[204:207], v193 offset:19456
	ds_read_b128 v[208:211], v193 offset:20480
	ds_read_b128 v[212:215], v193 offset:21504
	ds_read_b128 v[216:219], v193 offset:22528
	ds_read_b128 v[220:223], v193 offset:23552
	global_load_lds_dwordx4 v[224:225], off
	s_add_i32 m0, s64, 0x2000
	s_add_u32 s64, s4, 0x40000
	v_lshl_add_u64 v[226:227], s[4:5], 0, v[142:143]
	s_addc_u32 s65, s5, 0
	s_add_i32 s66, s60, s48
	global_load_lds_dwordx4 v[226:227], off
	v_lshl_add_u64 v[228:229], s[64:65], 0, v[138:139]
	s_mov_b32 m0, s66
	v_lshl_add_u64 v[230:231], s[46:47], 0, v[140:141]
	global_load_lds_dwordx4 v[228:229], off
	v_lshl_add_u64 v[228:229], s[64:65], 0, v[142:143]
	s_add_i32 m0, s66, 0x2000
	s_nop 0
	global_load_lds_dwordx4 v[228:229], off
	v_lshl_add_u64 v[228:229], s[46:47], 0, v[136:137]
	s_mov_b32 m0, s49
	s_nop 0
	global_load_lds_dwordx4 v[228:229], off
	s_mov_b32 m0, s50
	s_nop 0
	global_load_lds_dwordx4 v[230:231], off
	s_waitcnt vmcnt(8)
	s_waitcnt lgkmcnt(0)
	s_barrier
	s_waitcnt lgkmcnt(0)
	v_mfma_f32_16x16x32_bf16 v[60:63], v[128:131], v[180:183], v[60:63]
	v_mfma_f32_16x16x32_bf16 v[56:59], v[156:159], v[180:183], v[56:59]
	v_mfma_f32_16x16x32_bf16 v[44:47], v[128:131], v[198:201], v[44:47]
	v_mfma_f32_16x16x32_bf16 v[40:43], v[156:159], v[198:201], v[40:43]
	v_mfma_f32_16x16x32_bf16 v[28:31], v[128:131], v[208:211], v[28:31]
	v_mfma_f32_16x16x32_bf16 v[24:27], v[156:159], v[208:211], v[24:27]
	v_mfma_f32_16x16x32_bf16 v[12:15], v[128:131], v[216:219], v[12:15]
	v_mfma_f32_16x16x32_bf16 v[8:11], v[156:159], v[216:219], v[8:11]
	v_mfma_f32_16x16x32_bf16 v[60:63], v[132:135], v[184:187], v[60:63]
	v_mfma_f32_16x16x32_bf16 v[56:59], v[160:163], v[184:187], v[56:59]
	v_mfma_f32_16x16x32_bf16 v[44:47], v[132:135], v[204:207], v[44:47]
	v_mfma_f32_16x16x32_bf16 v[40:43], v[160:163], v[204:207], v[40:43]
	v_mfma_f32_16x16x32_bf16 v[28:31], v[132:135], v[212:215], v[28:31]
	v_mfma_f32_16x16x32_bf16 v[24:27], v[160:163], v[212:215], v[24:27]
	v_mfma_f32_16x16x32_bf16 v[12:15], v[132:135], v[220:223], v[12:15]
	v_mfma_f32_16x16x32_bf16 v[8:11], v[160:163], v[220:223], v[8:11]
	v_mfma_f32_16x16x32_bf16 v[52:55], v[164:167], v[180:183], v[52:55]
	v_mfma_f32_16x16x32_bf16 v[48:51], v[172:175], v[180:183], v[48:51]
	v_mfma_f32_16x16x32_bf16 v[36:39], v[164:167], v[198:201], v[36:39]
	v_mfma_f32_16x16x32_bf16 v[32:35], v[172:175], v[198:201], v[32:35]
	v_mfma_f32_16x16x32_bf16 v[20:23], v[164:167], v[208:211], v[20:23]
	v_mfma_f32_16x16x32_bf16 v[16:19], v[172:175], v[208:211], v[16:19]
	v_mfma_f32_16x16x32_bf16 v[4:7], v[164:167], v[216:219], v[4:7]
	v_mfma_f32_16x16x32_bf16 v[0:3], v[172:175], v[216:219], v[0:3]
	v_mfma_f32_16x16x32_bf16 v[52:55], v[168:171], v[184:187], v[52:55]
	v_mfma_f32_16x16x32_bf16 v[48:51], v[176:179], v[184:187], v[48:51]
	v_mfma_f32_16x16x32_bf16 v[36:39], v[168:171], v[204:207], v[36:39]
	v_mfma_f32_16x16x32_bf16 v[32:35], v[176:179], v[204:207], v[32:35]
	v_mfma_f32_16x16x32_bf16 v[20:23], v[168:171], v[212:215], v[20:23]
	v_mfma_f32_16x16x32_bf16 v[16:19], v[176:179], v[212:215], v[16:19]
	v_mfma_f32_16x16x32_bf16 v[4:7], v[168:171], v[220:223], v[4:7]
	v_mfma_f32_16x16x32_bf16 v[0:3], v[176:179], v[220:223], v[0:3]
	s_barrier
	s_add_i32 s64, 0, 0x18000
	v_add_u32_e32 v144, s64, v189
	s_add_i32 s65, 0, 0x1c000
	ds_read_b128 v[128:131], v144
	ds_read_b128 v[132:135], v144 offset:1024
	ds_read_b128 v[156:159], v144 offset:2048
	ds_read_b128 v[160:163], v144 offset:3072
	v_add_u32_e32 v144, s65, v189
	ds_read_b128 v[164:167], v144
	ds_read_b128 v[168:171], v144 offset:1024
	ds_read_b128 v[172:175], v144 offset:2048
	ds_read_b128 v[176:179], v144 offset:3072
	s_add_u32 s46, s46, 0x40000
	s_addc_u32 s47, s47, 0
	s_mov_b32 m0, s51
	v_lshl_add_u64 v[232:233], s[46:47], 0, v[136:137]
	ds_read_b128 v[180:183], v193 offset:32768
	ds_read_b128 v[184:187], v193 offset:33792
	ds_read_b128 v[198:201], v193 offset:34816
	ds_read_b128 v[204:207], v193 offset:35840
	ds_read_b128 v[208:211], v193 offset:36864
	ds_read_b128 v[212:215], v193 offset:37888
	ds_read_b128 v[216:219], v193 offset:38912
	ds_read_b128 v[220:223], v193 offset:39936
	global_load_lds_dwordx4 v[232:233], off
	v_lshl_add_u64 v[232:233], s[46:47], 0, v[140:141]
	s_mov_b32 m0, s52
	s_nop 0
	global_load_lds_dwordx4 v[232:233], off
	s_waitcnt vmcnt(8)
	s_waitcnt lgkmcnt(0)
	s_barrier
	s_waitcnt lgkmcnt(0)
	v_mfma_f32_16x16x32_bf16 v[124:127], v[128:131], v[180:183], v[124:127]
	v_mfma_f32_16x16x32_bf16 v[120:123], v[156:159], v[180:183], v[120:123]
	v_mfma_f32_16x16x32_bf16 v[108:111], v[128:131], v[198:201], v[108:111]
	v_mfma_f32_16x16x32_bf16 v[104:107], v[156:159], v[198:201], v[104:107]
	v_mfma_f32_16x16x32_bf16 v[92:95], v[128:131], v[208:211], v[92:95]
	v_mfma_f32_16x16x32_bf16 v[88:91], v[156:159], v[208:211], v[88:91]
	v_mfma_f32_16x16x32_bf16 v[76:79], v[128:131], v[216:219], v[76:79]
	v_mfma_f32_16x16x32_bf16 v[72:75], v[156:159], v[216:219], v[72:75]
	v_mfma_f32_16x16x32_bf16 v[124:127], v[132:135], v[184:187], v[124:127]
	v_mfma_f32_16x16x32_bf16 v[120:123], v[160:163], v[184:187], v[120:123]
	v_mfma_f32_16x16x32_bf16 v[108:111], v[132:135], v[204:207], v[108:111]
	v_mfma_f32_16x16x32_bf16 v[104:107], v[160:163], v[204:207], v[104:107]
	v_mfma_f32_16x16x32_bf16 v[92:95], v[132:135], v[212:215], v[92:95]
	v_mfma_f32_16x16x32_bf16 v[88:91], v[160:163], v[212:215], v[88:91]
	v_mfma_f32_16x16x32_bf16 v[76:79], v[132:135], v[220:223], v[76:79]
	v_mfma_f32_16x16x32_bf16 v[72:75], v[160:163], v[220:223], v[72:75]
	v_mfma_f32_16x16x32_bf16 v[116:119], v[164:167], v[180:183], v[116:119]
	v_mfma_f32_16x16x32_bf16 v[112:115], v[172:175], v[180:183], v[112:115]
	v_mfma_f32_16x16x32_bf16 v[100:103], v[164:167], v[198:201], v[100:103]
	v_mfma_f32_16x16x32_bf16 v[96:99], v[172:175], v[198:201], v[96:99]
	v_mfma_f32_16x16x32_bf16 v[84:87], v[164:167], v[208:211], v[84:87]
	v_mfma_f32_16x16x32_bf16 v[80:83], v[172:175], v[208:211], v[80:83]
	v_mfma_f32_16x16x32_bf16 v[68:71], v[164:167], v[216:219], v[68:71]
	v_mfma_f32_16x16x32_bf16 v[64:67], v[172:175], v[216:219], v[64:67]
	v_mfma_f32_16x16x32_bf16 v[116:119], v[168:171], v[184:187], v[116:119]
	v_mfma_f32_16x16x32_bf16 v[112:115], v[176:179], v[184:187], v[112:115]
	v_mfma_f32_16x16x32_bf16 v[100:103], v[168:171], v[204:207], v[100:103]
	v_mfma_f32_16x16x32_bf16 v[96:99], v[176:179], v[204:207], v[96:99]
	v_mfma_f32_16x16x32_bf16 v[84:87], v[168:171], v[212:215], v[84:87]
	v_mfma_f32_16x16x32_bf16 v[80:83], v[176:179], v[212:215], v[80:83]
	v_mfma_f32_16x16x32_bf16 v[68:71], v[168:171], v[220:223], v[68:71]
	v_mfma_f32_16x16x32_bf16 v[64:67], v[176:179], v[220:223], v[64:67]
	s_barrier
	s_add_i32 s46, s64, s48
	v_lshl_add_u64 v[224:225], v[224:225], 0, s[30:31]
	s_mov_b32 m0, s46
	ds_read_b128 v[180:183], v193 offset:49152
	ds_read_b128 v[184:187], v193 offset:50176
	ds_read_b128 v[198:201], v193 offset:51200
	ds_read_b128 v[204:207], v193 offset:52224
	ds_read_b128 v[208:211], v193 offset:53248
	ds_read_b128 v[212:215], v193 offset:54272
	ds_read_b128 v[216:219], v193 offset:55296
	ds_read_b128 v[220:223], v193 offset:56320
	global_load_lds_dwordx4 v[224:225], off
	s_add_i32 m0, s46, 0x2000
	s_add_u32 s4, s4, 0x40080
	v_lshl_add_u64 v[224:225], v[226:227], 0, s[30:31]
	s_addc_u32 s5, s5, 0
	s_add_i32 s46, s65, s48
	global_load_lds_dwordx4 v[224:225], off
	v_lshl_add_u64 v[224:225], s[4:5], 0, v[138:139]
	s_mov_b32 m0, s46
	s_nop 0
	global_load_lds_dwordx4 v[224:225], off
	v_lshl_add_u64 v[224:225], s[4:5], 0, v[142:143]
	s_add_i32 m0, s46, 0x2000
	s_nop 0
	global_load_lds_dwordx4 v[224:225], off
	v_lshl_add_u64 v[224:225], v[228:229], 0, s[30:31]
	s_mov_b32 m0, s56
	s_nop 0
	global_load_lds_dwordx4 v[224:225], off
	v_lshl_add_u64 v[224:225], v[230:231], 0, s[30:31]
	s_mov_b32 m0, s57
	s_nop 0
	global_load_lds_dwordx4 v[224:225], off
	s_waitcnt vmcnt(8)
	s_waitcnt lgkmcnt(0)
	s_barrier
	s_waitcnt lgkmcnt(0)
	v_mfma_f32_16x16x32_bf16 v[60:63], v[128:131], v[180:183], v[60:63]
	v_mfma_f32_16x16x32_bf16 v[56:59], v[156:159], v[180:183], v[56:59]
	v_mfma_f32_16x16x32_bf16 v[44:47], v[128:131], v[198:201], v[44:47]
	v_mfma_f32_16x16x32_bf16 v[40:43], v[156:159], v[198:201], v[40:43]
	v_mfma_f32_16x16x32_bf16 v[28:31], v[128:131], v[208:211], v[28:31]
	v_mfma_f32_16x16x32_bf16 v[24:27], v[156:159], v[208:211], v[24:27]
	v_mfma_f32_16x16x32_bf16 v[12:15], v[128:131], v[216:219], v[12:15]
	v_mfma_f32_16x16x32_bf16 v[8:11], v[156:159], v[216:219], v[8:11]
	v_mfma_f32_16x16x32_bf16 v[60:63], v[132:135], v[184:187], v[60:63]
	v_mfma_f32_16x16x32_bf16 v[56:59], v[160:163], v[184:187], v[56:59]
	v_mfma_f32_16x16x32_bf16 v[44:47], v[132:135], v[204:207], v[44:47]
	v_mfma_f32_16x16x32_bf16 v[40:43], v[160:163], v[204:207], v[40:43]
	v_mfma_f32_16x16x32_bf16 v[28:31], v[132:135], v[212:215], v[28:31]
	v_mfma_f32_16x16x32_bf16 v[24:27], v[160:163], v[212:215], v[24:27]
	v_mfma_f32_16x16x32_bf16 v[12:15], v[132:135], v[220:223], v[12:15]
	v_mfma_f32_16x16x32_bf16 v[8:11], v[160:163], v[220:223], v[8:11]
	v_mfma_f32_16x16x32_bf16 v[52:55], v[164:167], v[180:183], v[52:55]
	v_mfma_f32_16x16x32_bf16 v[48:51], v[172:175], v[180:183], v[48:51]
	v_mfma_f32_16x16x32_bf16 v[36:39], v[164:167], v[198:201], v[36:39]
	v_mfma_f32_16x16x32_bf16 v[32:35], v[172:175], v[198:201], v[32:35]
	v_mfma_f32_16x16x32_bf16 v[20:23], v[164:167], v[208:211], v[20:23]
	v_mfma_f32_16x16x32_bf16 v[16:19], v[172:175], v[208:211], v[16:19]
	v_mfma_f32_16x16x32_bf16 v[4:7], v[164:167], v[216:219], v[4:7]
	v_mfma_f32_16x16x32_bf16 v[0:3], v[172:175], v[216:219], v[0:3]
	v_mfma_f32_16x16x32_bf16 v[52:55], v[168:171], v[184:187], v[52:55]
	v_mfma_f32_16x16x32_bf16 v[48:51], v[176:179], v[184:187], v[48:51]
	v_mfma_f32_16x16x32_bf16 v[36:39], v[168:171], v[204:207], v[36:39]
	v_mfma_f32_16x16x32_bf16 v[32:35], v[176:179], v[204:207], v[32:35]
	v_mfma_f32_16x16x32_bf16 v[20:23], v[168:171], v[212:215], v[20:23]
	v_mfma_f32_16x16x32_bf16 v[16:19], v[176:179], v[212:215], v[16:19]
	v_mfma_f32_16x16x32_bf16 v[4:7], v[168:171], v[220:223], v[4:7]
	v_mfma_f32_16x16x32_bf16 v[0:3], v[176:179], v[220:223], v[0:3]
	s_barrier
	s_add_i32 s63, s63, 2
	s_add_u32 s22, s22, 0x100
	s_addc_u32 s23, s23, 0
	s_add_u32 s41, s41, 0x100
	s_addc_u32 s62, s62, 0
	s_cmp_gt_u32 s63, 13
	s_cbranch_scc0 .LBB0_643
	s_and_b64 vcc, exec, s[34:35]
	s_cbranch_vccz .LBB0_646
	s_barrier

.LBB0_966:
	ds_read_b128 v[128:131], v189
	ds_read_b128 v[132:135], v189 offset:1024
	ds_read_b128 v[136:139], v189 offset:2048
	ds_read_b128 v[140:143], v189 offset:3072
	ds_read_b128 v[144:147], v190
	ds_read_b128 v[148:151], v190 offset:1024
	ds_read_b128 v[168:171], v190 offset:2048
	ds_read_b128 v[172:175], v190 offset:3072
	s_add_u32 s4, s22, 0xfffc0080
	s_addc_u32 s5, s23, -1
	s_cmp_eq_u32 s58, 12
	s_cselect_b32 s43, s35, s5
	s_cselect_b32 s42, s41, s4
	s_cselect_b32 s5, s31, s57
	s_cselect_b32 s4, s55, s56
	v_lshl_add_u64 v[184:185], s[22:23], 0, v[160:161]
	s_add_i32 m0, s46, 0xc000
	ds_read_b128 v[176:179], v191
	ds_read_b128 v[180:183], v191 offset:1024
	ds_read_b128 v[192:195], v191 offset:2048
	ds_read_b128 v[198:201], v191 offset:3072
	ds_read_b128 v[204:207], v191 offset:4096
	ds_read_b128 v[208:211], v191 offset:5120
	ds_read_b128 v[212:215], v191 offset:6144
	ds_read_b128 v[216:219], v191 offset:7168
	global_load_lds_dwordx4 v[184:185], off
	v_lshl_add_u64 v[184:185], s[22:23], 0, v[162:163]
	s_add_i32 m0, s46, 0xe000
	s_nop 0
	global_load_lds_dwordx4 v[184:185], off
	s_waitcnt vmcnt(8)
	s_waitcnt lgkmcnt(0)
	s_barrier
	s_waitcnt lgkmcnt(0)
	v_mfma_f32_16x16x32_bf16 v[124:127], v[128:131], v[176:179], v[124:127]
	v_mfma_f32_16x16x32_bf16 v[120:123], v[136:139], v[176:179], v[120:123]
	v_mfma_f32_16x16x32_bf16 v[108:111], v[128:131], v[192:195], v[108:111]
	v_mfma_f32_16x16x32_bf16 v[104:107], v[136:139], v[192:195], v[104:107]
	v_mfma_f32_16x16x32_bf16 v[92:95], v[128:131], v[204:207], v[92:95]
	v_mfma_f32_16x16x32_bf16 v[88:91], v[136:139], v[204:207], v[88:91]
	v_mfma_f32_16x16x32_bf16 v[76:79], v[128:131], v[212:215], v[76:79]
	v_mfma_f32_16x16x32_bf16 v[72:75], v[136:139], v[212:215], v[72:75]
	v_mfma_f32_16x16x32_bf16 v[124:127], v[132:135], v[180:183], v[124:127]
	v_mfma_f32_16x16x32_bf16 v[120:123], v[140:143], v[180:183], v[120:123]
	v_mfma_f32_16x16x32_bf16 v[108:111], v[132:135], v[198:201], v[108:111]
	v_mfma_f32_16x16x32_bf16 v[104:107], v[140:143], v[198:201], v[104:107]
	v_mfma_f32_16x16x32_bf16 v[92:95], v[132:135], v[208:211], v[92:95]
	v_mfma_f32_16x16x32_bf16 v[88:91], v[140:143], v[208:211], v[88:91]
	v_mfma_f32_16x16x32_bf16 v[76:79], v[132:135], v[216:219], v[76:79]
	v_mfma_f32_16x16x32_bf16 v[72:75], v[140:143], v[216:219], v[72:75]
	v_mfma_f32_16x16x32_bf16 v[116:119], v[144:147], v[176:179], v[116:119]
	v_mfma_f32_16x16x32_bf16 v[112:115], v[168:171], v[176:179], v[112:115]
	v_mfma_f32_16x16x32_bf16 v[100:103], v[144:147], v[192:195], v[100:103]
	v_mfma_f32_16x16x32_bf16 v[96:99], v[168:171], v[192:195], v[96:99]
	v_mfma_f32_16x16x32_bf16 v[84:87], v[144:147], v[204:207], v[84:87]
	v_mfma_f32_16x16x32_bf16 v[80:83], v[168:171], v[204:207], v[80:83]
	v_mfma_f32_16x16x32_bf16 v[68:71], v[144:147], v[212:215], v[68:71]
	v_mfma_f32_16x16x32_bf16 v[64:67], v[168:171], v[212:215], v[64:67]
	v_mfma_f32_16x16x32_bf16 v[116:119], v[148:151], v[180:183], v[116:119]
	v_mfma_f32_16x16x32_bf16 v[112:115], v[172:175], v[180:183], v[112:115]
	v_mfma_f32_16x16x32_bf16 v[100:103], v[148:151], v[198:201], v[100:103]
	v_mfma_f32_16x16x32_bf16 v[96:99], v[172:175], v[198:201], v[96:99]
	v_mfma_f32_16x16x32_bf16 v[84:87], v[148:151], v[208:211], v[84:87]
	v_mfma_f32_16x16x32_bf16 v[80:83], v[172:175], v[208:211], v[80:83]
	v_mfma_f32_16x16x32_bf16 v[68:71], v[148:151], v[216:219], v[68:71]
	v_mfma_f32_16x16x32_bf16 v[64:67], v[172:175], v[216:219], v[64:67]
	s_barrier
	s_add_i32 s59, s52, s45
	v_lshl_add_u64 v[184:185], s[4:5], 0, v[154:155]
	s_mov_b32 m0, s59
	ds_read_b128 v[176:179], v191 offset:16384
	ds_read_b128 v[180:183], v191 offset:17408
	ds_read_b128 v[192:195], v191 offset:18432
	ds_read_b128 v[198:201], v191 offset:19456
	ds_read_b128 v[204:207], v191 offset:20480
	ds_read_b128 v[208:211], v191 offset:21504
	ds_read_b128 v[212:215], v191 offset:22528
	ds_read_b128 v[216:219], v191 offset:23552
	global_load_lds_dwordx4 v[184:185], off
	s_add_i32 m0, s59, 0x2000
	s_add_u32 s60, s4, 0x40000
	v_lshl_add_u64 v[220:221], s[4:5], 0, v[158:159]
	s_addc_u32 s61, s5, 0
	s_add_i32 s59, s53, s45
	global_load_lds_dwordx4 v[220:221], off
	v_lshl_add_u64 v[222:223], s[60:61], 0, v[154:155]
	s_mov_b32 m0, s59
	v_lshl_add_u64 v[224:225], s[42:43], 0, v[156:157]
	global_load_lds_dwordx4 v[222:223], off
	v_lshl_add_u64 v[222:223], s[60:61], 0, v[158:159]
	s_add_i32 m0, s59, 0x2000
	s_nop 0
	global_load_lds_dwordx4 v[222:223], off
	v_lshl_add_u64 v[222:223], s[42:43], 0, v[152:153]
	s_mov_b32 m0, s46
	s_nop 0
	global_load_lds_dwordx4 v[222:223], off
	s_mov_b32 m0, s33
	s_nop 0
	global_load_lds_dwordx4 v[224:225], off
	s_waitcnt vmcnt(8)
	s_waitcnt lgkmcnt(0)
	s_barrier
	s_waitcnt lgkmcnt(0)
	v_mfma_f32_16x16x32_bf16 v[60:63], v[128:131], v[176:179], v[60:63]
	v_mfma_f32_16x16x32_bf16 v[56:59], v[136:139], v[176:179], v[56:59]
	v_mfma_f32_16x16x32_bf16 v[44:47], v[128:131], v[192:195], v[44:47]
	v_mfma_f32_16x16x32_bf16 v[40:43], v[136:139], v[192:195], v[40:43]
	v_mfma_f32_16x16x32_bf16 v[28:31], v[128:131], v[204:207], v[28:31]
	v_mfma_f32_16x16x32_bf16 v[24:27], v[136:139], v[204:207], v[24:27]
	v_mfma_f32_16x16x32_bf16 v[12:15], v[128:131], v[212:215], v[12:15]
	v_mfma_f32_16x16x32_bf16 v[8:11], v[136:139], v[212:215], v[8:11]
	v_mfma_f32_16x16x32_bf16 v[60:63], v[132:135], v[180:183], v[60:63]
	v_mfma_f32_16x16x32_bf16 v[56:59], v[140:143], v[180:183], v[56:59]
	v_mfma_f32_16x16x32_bf16 v[44:47], v[132:135], v[198:201], v[44:47]
	v_mfma_f32_16x16x32_bf16 v[40:43], v[140:143], v[198:201], v[40:43]
	v_mfma_f32_16x16x32_bf16 v[28:31], v[132:135], v[208:211], v[28:31]
	v_mfma_f32_16x16x32_bf16 v[24:27], v[140:143], v[208:211], v[24:27]
	v_mfma_f32_16x16x32_bf16 v[12:15], v[132:135], v[216:219], v[12:15]
	v_mfma_f32_16x16x32_bf16 v[8:11], v[140:143], v[216:219], v[8:11]
	v_mfma_f32_16x16x32_bf16 v[52:55], v[144:147], v[176:179], v[52:55]
	v_mfma_f32_16x16x32_bf16 v[48:51], v[168:171], v[176:179], v[48:51]
	v_mfma_f32_16x16x32_bf16 v[36:39], v[144:147], v[192:195], v[36:39]
	v_mfma_f32_16x16x32_bf16 v[32:35], v[168:171], v[192:195], v[32:35]
	v_mfma_f32_16x16x32_bf16 v[20:23], v[144:147], v[204:207], v[20:23]
	v_mfma_f32_16x16x32_bf16 v[16:19], v[168:171], v[204:207], v[16:19]
	v_mfma_f32_16x16x32_bf16 v[4:7], v[144:147], v[212:215], v[4:7]
	v_mfma_f32_16x16x32_bf16 v[0:3], v[168:171], v[212:215], v[0:3]
	v_mfma_f32_16x16x32_bf16 v[52:55], v[148:151], v[180:183], v[52:55]
	v_mfma_f32_16x16x32_bf16 v[48:51], v[172:175], v[180:183], v[48:51]
	v_mfma_f32_16x16x32_bf16 v[36:39], v[148:151], v[198:201], v[36:39]
	v_mfma_f32_16x16x32_bf16 v[32:35], v[172:175], v[198:201], v[32:35]
	v_mfma_f32_16x16x32_bf16 v[20:23], v[148:151], v[208:211], v[20:23]
	v_mfma_f32_16x16x32_bf16 v[16:19], v[172:175], v[208:211], v[16:19]
	v_mfma_f32_16x16x32_bf16 v[4:7], v[148:151], v[216:219], v[4:7]
	v_mfma_f32_16x16x32_bf16 v[0:3], v[172:175], v[216:219], v[0:3]
	s_barrier
	s_add_i32 s59, 0, 0x18000
	s_add_i32 s60, 0, 0x1c000
	v_add_u32_e32 v140, s59, v187
	v_add_u32_e32 v172, s60, v187
	ds_read_b128 v[128:131], v140
	ds_read_b128 v[132:135], v140 offset:1024
	ds_read_b128 v[136:139], v140 offset:2048
	ds_read_b128 v[140:143], v140 offset:3072
	ds_read_b128 v[144:147], v172
	ds_read_b128 v[148:151], v172 offset:1024
	ds_read_b128 v[168:171], v172 offset:2048
	ds_read_b128 v[172:175], v172 offset:3072
	s_add_u32 s42, s42, 0x40000
	s_addc_u32 s43, s43, 0
	s_mov_b32 m0, s47
	v_lshl_add_u64 v[226:227], s[42:43], 0, v[152:153]
	ds_read_b128 v[176:179], v191 offset:32768
	ds_read_b128 v[180:183], v191 offset:33792
	ds_read_b128 v[192:195], v191 offset:34816
	ds_read_b128 v[198:201], v191 offset:35840
	ds_read_b128 v[204:207], v191 offset:36864
	ds_read_b128 v[208:211], v191 offset:37888
	ds_read_b128 v[212:215], v191 offset:38912
	ds_read_b128 v[216:219], v191 offset:39936
	global_load_lds_dwordx4 v[226:227], off
	v_lshl_add_u64 v[226:227], s[42:43], 0, v[156:157]
	s_mov_b32 m0, s48
	s_nop 0
	global_load_lds_dwordx4 v[226:227], off
	s_waitcnt vmcnt(8)
	s_waitcnt lgkmcnt(0)
	s_barrier
	s_waitcnt lgkmcnt(0)
	v_mfma_f32_16x16x32_bf16 v[124:127], v[128:131], v[176:179], v[124:127]
	v_mfma_f32_16x16x32_bf16 v[120:123], v[136:139], v[176:179], v[120:123]
	v_mfma_f32_16x16x32_bf16 v[108:111], v[128:131], v[192:195], v[108:111]
	v_mfma_f32_16x16x32_bf16 v[104:107], v[136:139], v[192:195], v[104:107]
	v_mfma_f32_16x16x32_bf16 v[92:95], v[128:131], v[204:207], v[92:95]
	v_mfma_f32_16x16x32_bf16 v[88:91], v[136:139], v[204:207], v[88:91]
	v_mfma_f32_16x16x32_bf16 v[76:79], v[128:131], v[212:215], v[76:79]
	v_mfma_f32_16x16x32_bf16 v[72:75], v[136:139], v[212:215], v[72:75]
	v_mfma_f32_16x16x32_bf16 v[124:127], v[132:135], v[180:183], v[124:127]
	v_mfma_f32_16x16x32_bf16 v[120:123], v[140:143], v[180:183], v[120:123]
	v_mfma_f32_16x16x32_bf16 v[108:111], v[132:135], v[198:201], v[108:111]
	v_mfma_f32_16x16x32_bf16 v[104:107], v[140:143], v[198:201], v[104:107]
	v_mfma_f32_16x16x32_bf16 v[92:95], v[132:135], v[208:211], v[92:95]
	v_mfma_f32_16x16x32_bf16 v[88:91], v[140:143], v[208:211], v[88:91]
	v_mfma_f32_16x16x32_bf16 v[76:79], v[132:135], v[216:219], v[76:79]
	v_mfma_f32_16x16x32_bf16 v[72:75], v[140:143], v[216:219], v[72:75]
	v_mfma_f32_16x16x32_bf16 v[116:119], v[144:147], v[176:179], v[116:119]
	v_mfma_f32_16x16x32_bf16 v[112:115], v[168:171], v[176:179], v[112:115]
	v_mfma_f32_16x16x32_bf16 v[100:103], v[144:147], v[192:195], v[100:103]
	v_mfma_f32_16x16x32_bf16 v[96:99], v[168:171], v[192:195], v[96:99]
	v_mfma_f32_16x16x32_bf16 v[84:87], v[144:147], v[204:207], v[84:87]
	v_mfma_f32_16x16x32_bf16 v[80:83], v[168:171], v[204:207], v[80:83]
	v_mfma_f32_16x16x32_bf16 v[68:71], v[144:147], v[212:215], v[68:71]
	v_mfma_f32_16x16x32_bf16 v[64:67], v[168:171], v[212:215], v[64:67]
	v_mfma_f32_16x16x32_bf16 v[116:119], v[148:151], v[180:183], v[116:119]
	v_mfma_f32_16x16x32_bf16 v[112:115], v[172:175], v[180:183], v[112:115]
	v_mfma_f32_16x16x32_bf16 v[100:103], v[148:151], v[198:201], v[100:103]
	v_mfma_f32_16x16x32_bf16 v[96:99], v[172:175], v[198:201], v[96:99]
	v_mfma_f32_16x16x32_bf16 v[84:87], v[148:151], v[208:211], v[84:87]
	v_mfma_f32_16x16x32_bf16 v[80:83], v[172:175], v[208:211], v[80:83]
	v_mfma_f32_16x16x32_bf16 v[68:71], v[148:151], v[216:219], v[68:71]
	v_mfma_f32_16x16x32_bf16 v[64:67], v[172:175], v[216:219], v[64:67]
	s_barrier
	s_add_i32 s42, s59, s45
	v_lshl_add_u64 v[184:185], v[184:185], 0, s[26:27]
	s_mov_b32 m0, s42
	ds_read_b128 v[176:179], v191 offset:49152
	ds_read_b128 v[180:183], v191 offset:50176
	ds_read_b128 v[192:195], v191 offset:51200
	ds_read_b128 v[198:201], v191 offset:52224
	ds_read_b128 v[204:207], v191 offset:53248
	ds_read_b128 v[208:211], v191 offset:54272
	ds_read_b128 v[212:215], v191 offset:55296
	ds_read_b128 v[216:219], v191 offset:56320
	global_load_lds_dwordx4 v[184:185], off
	s_add_i32 m0, s42, 0x2000
	s_add_u32 s4, s4, 0x40080
	v_lshl_add_u64 v[184:185], v[220:221], 0, s[26:27]
	s_addc_u32 s5, s5, 0
	s_add_i32 s42, s60, s45
	global_load_lds_dwordx4 v[184:185], off
	v_lshl_add_u64 v[184:185], s[4:5], 0, v[154:155]
	s_mov_b32 m0, s42
	s_nop 0
	global_load_lds_dwordx4 v[184:185], off
	v_lshl_add_u64 v[184:185], s[4:5], 0, v[158:159]
	s_add_i32 m0, s42, 0x2000
	s_nop 0
	global_load_lds_dwordx4 v[184:185], off
	v_lshl_add_u64 v[184:185], v[222:223], 0, s[26:27]
	s_mov_b32 m0, s50
	s_nop 0
	global_load_lds_dwordx4 v[184:185], off
	v_lshl_add_u64 v[184:185], v[224:225], 0, s[26:27]
	s_mov_b32 m0, s51
	s_nop 0
	global_load_lds_dwordx4 v[184:185], off
	s_waitcnt vmcnt(8)
	s_waitcnt lgkmcnt(0)
	s_barrier
	s_waitcnt lgkmcnt(0)
	v_mfma_f32_16x16x32_bf16 v[60:63], v[128:131], v[176:179], v[60:63]
	v_mfma_f32_16x16x32_bf16 v[56:59], v[136:139], v[176:179], v[56:59]
	v_mfma_f32_16x16x32_bf16 v[44:47], v[128:131], v[192:195], v[44:47]
	v_mfma_f32_16x16x32_bf16 v[40:43], v[136:139], v[192:195], v[40:43]
	v_mfma_f32_16x16x32_bf16 v[28:31], v[128:131], v[204:207], v[28:31]
	v_mfma_f32_16x16x32_bf16 v[24:27], v[136:139], v[204:207], v[24:27]
	v_mfma_f32_16x16x32_bf16 v[12:15], v[128:131], v[212:215], v[12:15]
	v_mfma_f32_16x16x32_bf16 v[8:11], v[136:139], v[212:215], v[8:11]
	v_mfma_f32_16x16x32_bf16 v[60:63], v[132:135], v[180:183], v[60:63]
	v_mfma_f32_16x16x32_bf16 v[56:59], v[140:143], v[180:183], v[56:59]
	v_mfma_f32_16x16x32_bf16 v[44:47], v[132:135], v[198:201], v[44:47]
	v_mfma_f32_16x16x32_bf16 v[40:43], v[140:143], v[198:201], v[40:43]
	v_mfma_f32_16x16x32_bf16 v[28:31], v[132:135], v[208:211], v[28:31]
	v_mfma_f32_16x16x32_bf16 v[24:27], v[140:143], v[208:211], v[24:27]
	v_mfma_f32_16x16x32_bf16 v[12:15], v[132:135], v[216:219], v[12:15]
	v_mfma_f32_16x16x32_bf16 v[8:11], v[140:143], v[216:219], v[8:11]
	v_mfma_f32_16x16x32_bf16 v[52:55], v[144:147], v[176:179], v[52:55]
	v_mfma_f32_16x16x32_bf16 v[48:51], v[168:171], v[176:179], v[48:51]
	v_mfma_f32_16x16x32_bf16 v[36:39], v[144:147], v[192:195], v[36:39]
	v_mfma_f32_16x16x32_bf16 v[32:35], v[168:171], v[192:195], v[32:35]
	v_mfma_f32_16x16x32_bf16 v[20:23], v[144:147], v[204:207], v[20:23]
	v_mfma_f32_16x16x32_bf16 v[16:19], v[168:171], v[204:207], v[16:19]
	v_mfma_f32_16x16x32_bf16 v[4:7], v[144:147], v[212:215], v[4:7]
	v_mfma_f32_16x16x32_bf16 v[0:3], v[168:171], v[212:215], v[0:3]
	v_mfma_f32_16x16x32_bf16 v[52:55], v[148:151], v[180:183], v[52:55]
	v_mfma_f32_16x16x32_bf16 v[48:51], v[172:175], v[180:183], v[48:51]
	v_mfma_f32_16x16x32_bf16 v[36:39], v[148:151], v[198:201], v[36:39]
	v_mfma_f32_16x16x32_bf16 v[32:35], v[172:175], v[198:201], v[32:35]
	v_mfma_f32_16x16x32_bf16 v[20:23], v[148:151], v[208:211], v[20:23]
	v_mfma_f32_16x16x32_bf16 v[16:19], v[172:175], v[208:211], v[16:19]
	v_mfma_f32_16x16x32_bf16 v[4:7], v[148:151], v[216:219], v[4:7]
	v_mfma_f32_16x16x32_bf16 v[0:3], v[172:175], v[216:219], v[0:3]
	s_barrier
	s_add_i32 s58, s58, 2
	s_add_u32 s22, s22, 0x100
	s_addc_u32 s23, s23, 0
	s_add_u32 s56, s56, 0x100
	s_addc_u32 s57, s57, 0
	s_cmp_gt_u32 s58, 13
	s_cbranch_scc0 .LBB0_966
	s_and_b64 vcc, exec, s[28:29]
	s_cbranch_vccz .LBB0_969
	s_barrier

.LBB0_1048:
	ds_read_b128 v[146:149], v169
	ds_read_b128 v[150:153], v169 offset:1024
	ds_read_b128 v[154:157], v169 offset:2048
	ds_read_b128 v[160:163], v169 offset:3072
	ds_read_b128 v[178:181], v171
	ds_read_b128 v[182:185], v171 offset:1024
	ds_read_b128 v[186:189], v171 offset:2048
	ds_read_b128 v[190:193], v171 offset:3072
	s_add_u32 s4, s10, 0xfffc0080
	s_addc_u32 s5, s11, -1
	s_cmp_eq_u32 s55, 12
	s_cselect_b32 s13, s9, s5
	s_cselect_b32 s12, s31, s4
	s_cselect_b32 s5, s29, s54
	s_cselect_b32 s4, s52, s53
	v_lshl_add_u64 v[194:195], s[10:11], 0, v[138:139]
	s_add_i32 m0, s41, 0xc000
	ds_read_b128 v[198:201], v173
	ds_read_b128 v[204:207], v173 offset:1024
	ds_read_b128 v[208:211], v173 offset:2048
	ds_read_b128 v[212:215], v173 offset:3072
	ds_read_b128 v[216:219], v173 offset:4096
	ds_read_b128 v[220:223], v173 offset:5120
	ds_read_b128 v[224:227], v173 offset:6144
	ds_read_b128 v[228:231], v173 offset:7168
	global_load_lds_dwordx4 v[194:195], off
	v_lshl_add_u64 v[194:195], s[10:11], 0, v[140:141]
	s_add_i32 m0, s41, 0xe000
	s_nop 0
	global_load_lds_dwordx4 v[194:195], off
	s_waitcnt vmcnt(8)
	s_waitcnt lgkmcnt(0)
	s_barrier
	s_waitcnt lgkmcnt(0)
	v_mfma_f32_16x16x32_bf16 v[124:127], v[146:149], v[198:201], v[124:127]
	v_mfma_f32_16x16x32_bf16 v[116:119], v[154:157], v[198:201], v[116:119]
	v_mfma_f32_16x16x32_bf16 v[108:111], v[146:149], v[208:211], v[108:111]
	v_mfma_f32_16x16x32_bf16 v[100:103], v[154:157], v[208:211], v[100:103]
	v_mfma_f32_16x16x32_bf16 v[92:95], v[146:149], v[216:219], v[92:95]
	v_mfma_f32_16x16x32_bf16 v[84:87], v[154:157], v[216:219], v[84:87]
	v_mfma_f32_16x16x32_bf16 v[76:79], v[146:149], v[224:227], v[76:79]
	v_mfma_f32_16x16x32_bf16 v[68:71], v[154:157], v[224:227], v[68:71]
	v_mfma_f32_16x16x32_bf16 v[124:127], v[150:153], v[204:207], v[124:127]
	v_mfma_f32_16x16x32_bf16 v[116:119], v[160:163], v[204:207], v[116:119]
	v_mfma_f32_16x16x32_bf16 v[108:111], v[150:153], v[212:215], v[108:111]
	v_mfma_f32_16x16x32_bf16 v[100:103], v[160:163], v[212:215], v[100:103]
	v_mfma_f32_16x16x32_bf16 v[92:95], v[150:153], v[220:223], v[92:95]
	v_mfma_f32_16x16x32_bf16 v[84:87], v[160:163], v[220:223], v[84:87]
	v_mfma_f32_16x16x32_bf16 v[76:79], v[150:153], v[228:231], v[76:79]
	v_mfma_f32_16x16x32_bf16 v[68:71], v[160:163], v[228:231], v[68:71]
	v_mfma_f32_16x16x32_bf16 v[120:123], v[178:181], v[198:201], v[120:123]
	v_mfma_f32_16x16x32_bf16 v[112:115], v[186:189], v[198:201], v[112:115]
	v_mfma_f32_16x16x32_bf16 v[104:107], v[178:181], v[208:211], v[104:107]
	v_mfma_f32_16x16x32_bf16 v[96:99], v[186:189], v[208:211], v[96:99]
	v_mfma_f32_16x16x32_bf16 v[88:91], v[178:181], v[216:219], v[88:91]
	v_mfma_f32_16x16x32_bf16 v[80:83], v[186:189], v[216:219], v[80:83]
	v_mfma_f32_16x16x32_bf16 v[72:75], v[178:181], v[224:227], v[72:75]
	v_mfma_f32_16x16x32_bf16 v[64:67], v[186:189], v[224:227], v[64:67]
	v_mfma_f32_16x16x32_bf16 v[120:123], v[182:185], v[204:207], v[120:123]
	v_mfma_f32_16x16x32_bf16 v[112:115], v[190:193], v[204:207], v[112:115]
	v_mfma_f32_16x16x32_bf16 v[104:107], v[182:185], v[212:215], v[104:107]
	v_mfma_f32_16x16x32_bf16 v[96:99], v[190:193], v[212:215], v[96:99]
	v_mfma_f32_16x16x32_bf16 v[88:91], v[182:185], v[220:223], v[88:91]
	v_mfma_f32_16x16x32_bf16 v[80:83], v[190:193], v[220:223], v[80:83]
	v_mfma_f32_16x16x32_bf16 v[72:75], v[182:185], v[228:231], v[72:75]
	v_mfma_f32_16x16x32_bf16 v[64:67], v[190:193], v[228:231], v[64:67]
	s_barrier
	s_add_i32 s56, s48, s39
	v_lshl_add_u64 v[194:195], s[4:5], 0, v[132:133]
	s_mov_b32 m0, s56
	ds_read_b128 v[198:201], v173 offset:16384
	ds_read_b128 v[204:207], v173 offset:17408
	ds_read_b128 v[208:211], v173 offset:18432
	ds_read_b128 v[212:215], v173 offset:19456
	ds_read_b128 v[216:219], v173 offset:20480
	ds_read_b128 v[220:223], v173 offset:21504
	ds_read_b128 v[224:227], v173 offset:22528
	ds_read_b128 v[228:231], v173 offset:23552
	global_load_lds_dwordx4 v[194:195], off
	s_add_i32 m0, s56, 0x2000
	s_add_u32 s56, s4, 0x40000
	v_lshl_add_u64 v[232:233], s[4:5], 0, v[128:129]
	s_addc_u32 s57, s5, 0
	s_add_i32 s58, s49, s39
	global_load_lds_dwordx4 v[232:233], off
	v_lshl_add_u64 v[234:235], s[56:57], 0, v[132:133]
	s_mov_b32 m0, s58
	v_lshl_add_u64 v[236:237], s[12:13], 0, v[130:131]
	global_load_lds_dwordx4 v[234:235], off
	v_lshl_add_u64 v[234:235], s[56:57], 0, v[128:129]
	s_add_i32 m0, s58, 0x2000
	s_nop 0
	global_load_lds_dwordx4 v[234:235], off
	v_lshl_add_u64 v[234:235], s[12:13], 0, v[134:135]
	s_mov_b32 m0, s41
	s_nop 0
	global_load_lds_dwordx4 v[234:235], off
	s_mov_b32 m0, s42
	s_nop 0
	global_load_lds_dwordx4 v[236:237], off
	s_waitcnt vmcnt(8)
	s_waitcnt lgkmcnt(0)
	s_barrier
	s_waitcnt lgkmcnt(0)
	v_mfma_f32_16x16x32_bf16 v[60:63], v[146:149], v[198:201], v[60:63]
	v_mfma_f32_16x16x32_bf16 v[52:55], v[154:157], v[198:201], v[52:55]
	v_mfma_f32_16x16x32_bf16 v[44:47], v[146:149], v[208:211], v[44:47]
	v_mfma_f32_16x16x32_bf16 v[36:39], v[154:157], v[208:211], v[36:39]
	v_mfma_f32_16x16x32_bf16 v[28:31], v[146:149], v[216:219], v[28:31]
	v_mfma_f32_16x16x32_bf16 v[20:23], v[154:157], v[216:219], v[20:23]
	v_mfma_f32_16x16x32_bf16 v[12:15], v[146:149], v[224:227], v[12:15]
	v_mfma_f32_16x16x32_bf16 v[4:7], v[154:157], v[224:227], v[4:7]
	v_mfma_f32_16x16x32_bf16 v[60:63], v[150:153], v[204:207], v[60:63]
	v_mfma_f32_16x16x32_bf16 v[52:55], v[160:163], v[204:207], v[52:55]
	v_mfma_f32_16x16x32_bf16 v[44:47], v[150:153], v[212:215], v[44:47]
	v_mfma_f32_16x16x32_bf16 v[36:39], v[160:163], v[212:215], v[36:39]
	v_mfma_f32_16x16x32_bf16 v[28:31], v[150:153], v[220:223], v[28:31]
	v_mfma_f32_16x16x32_bf16 v[20:23], v[160:163], v[220:223], v[20:23]
	v_mfma_f32_16x16x32_bf16 v[12:15], v[150:153], v[228:231], v[12:15]
	v_mfma_f32_16x16x32_bf16 v[4:7], v[160:163], v[228:231], v[4:7]
	v_mfma_f32_16x16x32_bf16 v[56:59], v[178:181], v[198:201], v[56:59]
	v_mfma_f32_16x16x32_bf16 v[48:51], v[186:189], v[198:201], v[48:51]
	v_mfma_f32_16x16x32_bf16 v[40:43], v[178:181], v[208:211], v[40:43]
	v_mfma_f32_16x16x32_bf16 v[32:35], v[186:189], v[208:211], v[32:35]
	v_mfma_f32_16x16x32_bf16 v[24:27], v[178:181], v[216:219], v[24:27]
	v_mfma_f32_16x16x32_bf16 v[16:19], v[186:189], v[216:219], v[16:19]
	v_mfma_f32_16x16x32_bf16 v[8:11], v[178:181], v[224:227], v[8:11]
	v_mfma_f32_16x16x32_bf16 v[0:3], v[186:189], v[224:227], v[0:3]
	v_mfma_f32_16x16x32_bf16 v[56:59], v[182:185], v[204:207], v[56:59]
	v_mfma_f32_16x16x32_bf16 v[48:51], v[190:193], v[204:207], v[48:51]
	v_mfma_f32_16x16x32_bf16 v[40:43], v[182:185], v[212:215], v[40:43]
	v_mfma_f32_16x16x32_bf16 v[32:35], v[190:193], v[212:215], v[32:35]
	v_mfma_f32_16x16x32_bf16 v[24:27], v[182:185], v[220:223], v[24:27]
	v_mfma_f32_16x16x32_bf16 v[16:19], v[190:193], v[220:223], v[16:19]
	v_mfma_f32_16x16x32_bf16 v[8:11], v[182:185], v[228:231], v[8:11]
	v_mfma_f32_16x16x32_bf16 v[0:3], v[190:193], v[228:231], v[0:3]
	s_barrier
	s_add_i32 s56, 0, 0x18000
	v_add_u32_e32 v158, s56, v165
	s_add_i32 s57, 0, 0x1c000
	ds_read_b128 v[146:149], v158
	ds_read_b128 v[150:153], v158 offset:1024
	ds_read_b128 v[154:157], v158 offset:2048
	ds_read_b128 v[160:163], v158 offset:3072
	v_add_u32_e32 v158, s57, v165
	ds_read_b128 v[178:181], v158
	ds_read_b128 v[182:185], v158 offset:1024
	ds_read_b128 v[186:189], v158 offset:2048
	ds_read_b128 v[190:193], v158 offset:3072
	s_add_u32 s12, s12, 0x40000
	s_addc_u32 s13, s13, 0
	s_mov_b32 m0, s43
	v_lshl_add_u64 v[238:239], s[12:13], 0, v[134:135]
	ds_read_b128 v[198:201], v173 offset:32768
	ds_read_b128 v[204:207], v173 offset:33792
	ds_read_b128 v[208:211], v173 offset:34816
	ds_read_b128 v[212:215], v173 offset:35840
	ds_read_b128 v[216:219], v173 offset:36864
	ds_read_b128 v[220:223], v173 offset:37888
	ds_read_b128 v[224:227], v173 offset:38912
	ds_read_b128 v[228:231], v173 offset:39936
	global_load_lds_dwordx4 v[238:239], off
	v_lshl_add_u64 v[238:239], s[12:13], 0, v[130:131]
	s_mov_b32 m0, s44
	s_nop 0
	global_load_lds_dwordx4 v[238:239], off
	s_waitcnt vmcnt(8)
	s_waitcnt lgkmcnt(0)
	s_barrier
	s_waitcnt lgkmcnt(0)
	v_mfma_f32_16x16x32_bf16 v[124:127], v[146:149], v[198:201], v[124:127]
	v_mfma_f32_16x16x32_bf16 v[116:119], v[154:157], v[198:201], v[116:119]
	v_mfma_f32_16x16x32_bf16 v[108:111], v[146:149], v[208:211], v[108:111]
	v_mfma_f32_16x16x32_bf16 v[100:103], v[154:157], v[208:211], v[100:103]
	v_mfma_f32_16x16x32_bf16 v[92:95], v[146:149], v[216:219], v[92:95]
	v_mfma_f32_16x16x32_bf16 v[84:87], v[154:157], v[216:219], v[84:87]
	v_mfma_f32_16x16x32_bf16 v[76:79], v[146:149], v[224:227], v[76:79]
	v_mfma_f32_16x16x32_bf16 v[68:71], v[154:157], v[224:227], v[68:71]
	v_mfma_f32_16x16x32_bf16 v[124:127], v[150:153], v[204:207], v[124:127]
	v_mfma_f32_16x16x32_bf16 v[116:119], v[160:163], v[204:207], v[116:119]
	v_mfma_f32_16x16x32_bf16 v[108:111], v[150:153], v[212:215], v[108:111]
	v_mfma_f32_16x16x32_bf16 v[100:103], v[160:163], v[212:215], v[100:103]
	v_mfma_f32_16x16x32_bf16 v[92:95], v[150:153], v[220:223], v[92:95]
	v_mfma_f32_16x16x32_bf16 v[84:87], v[160:163], v[220:223], v[84:87]
	v_mfma_f32_16x16x32_bf16 v[76:79], v[150:153], v[228:231], v[76:79]
	v_mfma_f32_16x16x32_bf16 v[68:71], v[160:163], v[228:231], v[68:71]
	v_mfma_f32_16x16x32_bf16 v[120:123], v[178:181], v[198:201], v[120:123]
	v_mfma_f32_16x16x32_bf16 v[112:115], v[186:189], v[198:201], v[112:115]
	v_mfma_f32_16x16x32_bf16 v[104:107], v[178:181], v[208:211], v[104:107]
	v_mfma_f32_16x16x32_bf16 v[96:99], v[186:189], v[208:211], v[96:99]
	v_mfma_f32_16x16x32_bf16 v[88:91], v[178:181], v[216:219], v[88:91]
	v_mfma_f32_16x16x32_bf16 v[80:83], v[186:189], v[216:219], v[80:83]
	v_mfma_f32_16x16x32_bf16 v[72:75], v[178:181], v[224:227], v[72:75]
	v_mfma_f32_16x16x32_bf16 v[64:67], v[186:189], v[224:227], v[64:67]
	v_mfma_f32_16x16x32_bf16 v[120:123], v[182:185], v[204:207], v[120:123]
	v_mfma_f32_16x16x32_bf16 v[112:115], v[190:193], v[204:207], v[112:115]
	v_mfma_f32_16x16x32_bf16 v[104:107], v[182:185], v[212:215], v[104:107]
	v_mfma_f32_16x16x32_bf16 v[96:99], v[190:193], v[212:215], v[96:99]
	v_mfma_f32_16x16x32_bf16 v[88:91], v[182:185], v[220:223], v[88:91]
	v_mfma_f32_16x16x32_bf16 v[80:83], v[190:193], v[220:223], v[80:83]
	v_mfma_f32_16x16x32_bf16 v[72:75], v[182:185], v[228:231], v[72:75]
	v_mfma_f32_16x16x32_bf16 v[64:67], v[190:193], v[228:231], v[64:67]
	s_barrier
	s_add_i32 s12, s56, s39
	v_lshl_add_u64 v[194:195], v[194:195], 0, s[24:25]
	s_mov_b32 m0, s12
	ds_read_b128 v[198:201], v173 offset:49152
	ds_read_b128 v[204:207], v173 offset:50176
	ds_read_b128 v[208:211], v173 offset:51200
	ds_read_b128 v[212:215], v173 offset:52224
	ds_read_b128 v[216:219], v173 offset:53248
	ds_read_b128 v[220:223], v173 offset:54272
	ds_read_b128 v[224:227], v173 offset:55296
	ds_read_b128 v[228:231], v173 offset:56320
	global_load_lds_dwordx4 v[194:195], off
	s_add_i32 m0, s12, 0x2000
	s_add_u32 s4, s4, 0x40080
	v_lshl_add_u64 v[194:195], v[232:233], 0, s[24:25]
	s_addc_u32 s5, s5, 0
	s_add_i32 s12, s57, s39
	global_load_lds_dwordx4 v[194:195], off
	v_lshl_add_u64 v[194:195], s[4:5], 0, v[132:133]
	s_mov_b32 m0, s12
	s_nop 0
	global_load_lds_dwordx4 v[194:195], off
	v_lshl_add_u64 v[194:195], s[4:5], 0, v[128:129]
	s_add_i32 m0, s12, 0x2000
	s_nop 0
	global_load_lds_dwordx4 v[194:195], off
	v_lshl_add_u64 v[194:195], v[234:235], 0, s[24:25]
	s_mov_b32 m0, s46
	s_nop 0
	global_load_lds_dwordx4 v[194:195], off
	v_lshl_add_u64 v[194:195], v[236:237], 0, s[24:25]
	s_mov_b32 m0, s47
	s_nop 0
	global_load_lds_dwordx4 v[194:195], off
	s_waitcnt vmcnt(8)
	s_waitcnt lgkmcnt(0)
	s_barrier
	s_waitcnt lgkmcnt(0)
	v_mfma_f32_16x16x32_bf16 v[60:63], v[146:149], v[198:201], v[60:63]
	v_mfma_f32_16x16x32_bf16 v[52:55], v[154:157], v[198:201], v[52:55]
	v_mfma_f32_16x16x32_bf16 v[44:47], v[146:149], v[208:211], v[44:47]
	v_mfma_f32_16x16x32_bf16 v[36:39], v[154:157], v[208:211], v[36:39]
	v_mfma_f32_16x16x32_bf16 v[28:31], v[146:149], v[216:219], v[28:31]
	v_mfma_f32_16x16x32_bf16 v[20:23], v[154:157], v[216:219], v[20:23]
	v_mfma_f32_16x16x32_bf16 v[12:15], v[146:149], v[224:227], v[12:15]
	v_mfma_f32_16x16x32_bf16 v[4:7], v[154:157], v[224:227], v[4:7]
	v_mfma_f32_16x16x32_bf16 v[60:63], v[150:153], v[204:207], v[60:63]
	v_mfma_f32_16x16x32_bf16 v[52:55], v[160:163], v[204:207], v[52:55]
	v_mfma_f32_16x16x32_bf16 v[44:47], v[150:153], v[212:215], v[44:47]
	v_mfma_f32_16x16x32_bf16 v[36:39], v[160:163], v[212:215], v[36:39]
	v_mfma_f32_16x16x32_bf16 v[28:31], v[150:153], v[220:223], v[28:31]
	v_mfma_f32_16x16x32_bf16 v[20:23], v[160:163], v[220:223], v[20:23]
	v_mfma_f32_16x16x32_bf16 v[12:15], v[150:153], v[228:231], v[12:15]
	v_mfma_f32_16x16x32_bf16 v[4:7], v[160:163], v[228:231], v[4:7]
	v_mfma_f32_16x16x32_bf16 v[56:59], v[178:181], v[198:201], v[56:59]
	v_mfma_f32_16x16x32_bf16 v[48:51], v[186:189], v[198:201], v[48:51]
	v_mfma_f32_16x16x32_bf16 v[40:43], v[178:181], v[208:211], v[40:43]
	v_mfma_f32_16x16x32_bf16 v[32:35], v[186:189], v[208:211], v[32:35]
	v_mfma_f32_16x16x32_bf16 v[24:27], v[178:181], v[216:219], v[24:27]
	v_mfma_f32_16x16x32_bf16 v[16:19], v[186:189], v[216:219], v[16:19]
	v_mfma_f32_16x16x32_bf16 v[8:11], v[178:181], v[224:227], v[8:11]
	v_mfma_f32_16x16x32_bf16 v[0:3], v[186:189], v[224:227], v[0:3]
	v_mfma_f32_16x16x32_bf16 v[56:59], v[182:185], v[204:207], v[56:59]
	v_mfma_f32_16x16x32_bf16 v[48:51], v[190:193], v[204:207], v[48:51]
	v_mfma_f32_16x16x32_bf16 v[40:43], v[182:185], v[212:215], v[40:43]
	v_mfma_f32_16x16x32_bf16 v[32:35], v[190:193], v[212:215], v[32:35]
	v_mfma_f32_16x16x32_bf16 v[24:27], v[182:185], v[220:223], v[24:27]
	v_mfma_f32_16x16x32_bf16 v[16:19], v[190:193], v[220:223], v[16:19]
	v_mfma_f32_16x16x32_bf16 v[8:11], v[182:185], v[228:231], v[8:11]
	v_mfma_f32_16x16x32_bf16 v[0:3], v[190:193], v[228:231], v[0:3]
	s_barrier
	s_add_i32 s55, s55, 2
	s_add_u32 s10, s10, 0x100
	s_addc_u32 s11, s11, 0
	s_add_u32 s53, s53, 0x100
	s_addc_u32 s54, s54, 0
	s_cmp_gt_u32 s55, 13
	s_cbranch_scc0 .LBB0_1048
	s_and_b64 vcc, exec, s[26:27]
	s_cbranch_vccz .LBB0_1051
	s_barrier

.LBB0_1124:
	ds_read_b128 v[128:131], v189
	ds_read_b128 v[132:135], v189 offset:1024
	ds_read_b128 v[136:139], v189 offset:2048
	ds_read_b128 v[140:143], v189 offset:3072
	ds_read_b128 v[144:147], v190
	ds_read_b128 v[148:151], v190 offset:1024
	ds_read_b128 v[168:171], v190 offset:2048
	ds_read_b128 v[172:175], v190 offset:3072
	s_add_u32 s34, s30, 0x100
	s_addc_u32 s35, s31, 0
	s_cmp_eq_u32 s56, 40
	s_cselect_b32 s39, s9, s35
	s_cselect_b32 s38, s8, s34
	s_cselect_b32 s37, s29, s55
	s_cselect_b32 s36, s28, s54
	v_lshl_add_u64 v[184:185], s[30:31], 0, v[160:161]
	s_add_i32 m0, s42, 0xc000
	ds_read_b128 v[176:179], v191
	ds_read_b128 v[180:183], v191 offset:1024
	ds_read_b128 v[192:195], v191 offset:2048
	ds_read_b128 v[198:201], v191 offset:3072
	ds_read_b128 v[204:207], v191 offset:4096
	ds_read_b128 v[208:211], v191 offset:5120
	ds_read_b128 v[212:215], v191 offset:6144
	ds_read_b128 v[216:219], v191 offset:7168
	global_load_lds_dwordx4 v[184:185], off
	v_lshl_add_u64 v[184:185], s[30:31], 0, v[162:163]
	s_add_i32 m0, s42, 0xe000
	s_nop 0
	global_load_lds_dwordx4 v[184:185], off
	s_waitcnt vmcnt(8)
	s_waitcnt lgkmcnt(0)
	s_barrier
	s_waitcnt lgkmcnt(0)
	v_mfma_f32_16x16x32_bf16 v[124:127], v[128:131], v[176:179], v[124:127]
	v_mfma_f32_16x16x32_bf16 v[120:123], v[136:139], v[176:179], v[120:123]
	v_mfma_f32_16x16x32_bf16 v[108:111], v[128:131], v[192:195], v[108:111]
	v_mfma_f32_16x16x32_bf16 v[104:107], v[136:139], v[192:195], v[104:107]
	v_mfma_f32_16x16x32_bf16 v[92:95], v[128:131], v[204:207], v[92:95]
	v_mfma_f32_16x16x32_bf16 v[88:91], v[136:139], v[204:207], v[88:91]
	v_mfma_f32_16x16x32_bf16 v[76:79], v[128:131], v[212:215], v[76:79]
	v_mfma_f32_16x16x32_bf16 v[72:75], v[136:139], v[212:215], v[72:75]
	v_mfma_f32_16x16x32_bf16 v[124:127], v[132:135], v[180:183], v[124:127]
	v_mfma_f32_16x16x32_bf16 v[120:123], v[140:143], v[180:183], v[120:123]
	v_mfma_f32_16x16x32_bf16 v[108:111], v[132:135], v[198:201], v[108:111]
	v_mfma_f32_16x16x32_bf16 v[104:107], v[140:143], v[198:201], v[104:107]
	v_mfma_f32_16x16x32_bf16 v[92:95], v[132:135], v[208:211], v[92:95]
	v_mfma_f32_16x16x32_bf16 v[88:91], v[140:143], v[208:211], v[88:91]
	v_mfma_f32_16x16x32_bf16 v[76:79], v[132:135], v[216:219], v[76:79]
	v_mfma_f32_16x16x32_bf16 v[72:75], v[140:143], v[216:219], v[72:75]
	v_mfma_f32_16x16x32_bf16 v[116:119], v[144:147], v[176:179], v[116:119]
	v_mfma_f32_16x16x32_bf16 v[112:115], v[168:171], v[176:179], v[112:115]
	v_mfma_f32_16x16x32_bf16 v[100:103], v[144:147], v[192:195], v[100:103]
	v_mfma_f32_16x16x32_bf16 v[96:99], v[168:171], v[192:195], v[96:99]
	v_mfma_f32_16x16x32_bf16 v[84:87], v[144:147], v[204:207], v[84:87]
	v_mfma_f32_16x16x32_bf16 v[80:83], v[168:171], v[204:207], v[80:83]
	v_mfma_f32_16x16x32_bf16 v[68:71], v[144:147], v[212:215], v[68:71]
	v_mfma_f32_16x16x32_bf16 v[64:67], v[168:171], v[212:215], v[64:67]
	v_mfma_f32_16x16x32_bf16 v[116:119], v[148:151], v[180:183], v[116:119]
	v_mfma_f32_16x16x32_bf16 v[112:115], v[172:175], v[180:183], v[112:115]
	v_mfma_f32_16x16x32_bf16 v[100:103], v[148:151], v[198:201], v[100:103]
	v_mfma_f32_16x16x32_bf16 v[96:99], v[172:175], v[198:201], v[96:99]
	v_mfma_f32_16x16x32_bf16 v[84:87], v[148:151], v[208:211], v[84:87]
	v_mfma_f32_16x16x32_bf16 v[80:83], v[172:175], v[208:211], v[80:83]
	v_mfma_f32_16x16x32_bf16 v[68:71], v[148:151], v[216:219], v[68:71]
	v_mfma_f32_16x16x32_bf16 v[64:67], v[172:175], v[216:219], v[64:67]
	s_barrier
	s_add_i32 s30, s48, s41
	v_lshl_add_u64 v[184:185], s[36:37], 0, v[154:155]
	s_mov_b32 m0, s30
	ds_read_b128 v[176:179], v191 offset:16384
	ds_read_b128 v[180:183], v191 offset:17408
	ds_read_b128 v[192:195], v191 offset:18432
	ds_read_b128 v[198:201], v191 offset:19456
	ds_read_b128 v[204:207], v191 offset:20480
	ds_read_b128 v[208:211], v191 offset:21504
	ds_read_b128 v[212:215], v191 offset:22528
	ds_read_b128 v[216:219], v191 offset:23552
	global_load_lds_dwordx4 v[184:185], off
	s_add_i32 m0, s30, 0x2000
	s_add_u32 s30, s36, 0xb0000
	v_lshl_add_u64 v[220:221], s[36:37], 0, v[158:159]
	s_addc_u32 s31, s37, 0
	s_add_i32 s57, s49, s41
	global_load_lds_dwordx4 v[220:221], off
	v_lshl_add_u64 v[222:223], s[30:31], 0, v[154:155]
	s_mov_b32 m0, s57
	v_lshl_add_u64 v[224:225], s[38:39], 0, v[156:157]
	global_load_lds_dwordx4 v[222:223], off
	v_lshl_add_u64 v[222:223], s[30:31], 0, v[158:159]
	s_add_i32 m0, s57, 0x2000
	s_nop 0
	global_load_lds_dwordx4 v[222:223], off
	v_lshl_add_u64 v[222:223], s[38:39], 0, v[152:153]
	s_mov_b32 m0, s42
	s_nop 0
	global_load_lds_dwordx4 v[222:223], off
	s_mov_b32 m0, s33
	s_nop 0
	global_load_lds_dwordx4 v[224:225], off
	s_waitcnt vmcnt(8)
	s_waitcnt lgkmcnt(0)
	s_barrier
	s_waitcnt lgkmcnt(0)
	v_mfma_f32_16x16x32_bf16 v[60:63], v[128:131], v[176:179], v[60:63]
	v_mfma_f32_16x16x32_bf16 v[56:59], v[136:139], v[176:179], v[56:59]
	v_mfma_f32_16x16x32_bf16 v[44:47], v[128:131], v[192:195], v[44:47]
	v_mfma_f32_16x16x32_bf16 v[40:43], v[136:139], v[192:195], v[40:43]
	v_mfma_f32_16x16x32_bf16 v[28:31], v[128:131], v[204:207], v[28:31]
	v_mfma_f32_16x16x32_bf16 v[24:27], v[136:139], v[204:207], v[24:27]
	v_mfma_f32_16x16x32_bf16 v[12:15], v[128:131], v[212:215], v[12:15]
	v_mfma_f32_16x16x32_bf16 v[8:11], v[136:139], v[212:215], v[8:11]
	v_mfma_f32_16x16x32_bf16 v[60:63], v[132:135], v[180:183], v[60:63]
	v_mfma_f32_16x16x32_bf16 v[56:59], v[140:143], v[180:183], v[56:59]
	v_mfma_f32_16x16x32_bf16 v[44:47], v[132:135], v[198:201], v[44:47]
	v_mfma_f32_16x16x32_bf16 v[40:43], v[140:143], v[198:201], v[40:43]
	v_mfma_f32_16x16x32_bf16 v[28:31], v[132:135], v[208:211], v[28:31]
	v_mfma_f32_16x16x32_bf16 v[24:27], v[140:143], v[208:211], v[24:27]
	v_mfma_f32_16x16x32_bf16 v[12:15], v[132:135], v[216:219], v[12:15]
	v_mfma_f32_16x16x32_bf16 v[8:11], v[140:143], v[216:219], v[8:11]
	v_mfma_f32_16x16x32_bf16 v[52:55], v[144:147], v[176:179], v[52:55]
	v_mfma_f32_16x16x32_bf16 v[48:51], v[168:171], v[176:179], v[48:51]
	v_mfma_f32_16x16x32_bf16 v[36:39], v[144:147], v[192:195], v[36:39]
	v_mfma_f32_16x16x32_bf16 v[32:35], v[168:171], v[192:195], v[32:35]
	v_mfma_f32_16x16x32_bf16 v[20:23], v[144:147], v[204:207], v[20:23]
	v_mfma_f32_16x16x32_bf16 v[16:19], v[168:171], v[204:207], v[16:19]
	v_mfma_f32_16x16x32_bf16 v[4:7], v[144:147], v[212:215], v[4:7]
	v_mfma_f32_16x16x32_bf16 v[0:3], v[168:171], v[212:215], v[0:3]
	v_mfma_f32_16x16x32_bf16 v[52:55], v[148:151], v[180:183], v[52:55]
	v_mfma_f32_16x16x32_bf16 v[48:51], v[172:175], v[180:183], v[48:51]
	v_mfma_f32_16x16x32_bf16 v[36:39], v[148:151], v[198:201], v[36:39]
	v_mfma_f32_16x16x32_bf16 v[32:35], v[172:175], v[198:201], v[32:35]
	v_mfma_f32_16x16x32_bf16 v[20:23], v[148:151], v[208:211], v[20:23]
	v_mfma_f32_16x16x32_bf16 v[16:19], v[172:175], v[208:211], v[16:19]
	v_mfma_f32_16x16x32_bf16 v[4:7], v[148:151], v[216:219], v[4:7]
	v_mfma_f32_16x16x32_bf16 v[0:3], v[172:175], v[216:219], v[0:3]
	s_barrier
	s_add_i32 s57, 0, 0x18000
	s_add_i32 s58, 0, 0x1c000
	v_add_u32_e32 v140, s57, v187
	v_add_u32_e32 v172, s58, v187
	ds_read_b128 v[128:131], v140
	ds_read_b128 v[132:135], v140 offset:1024
	ds_read_b128 v[136:139], v140 offset:2048
	ds_read_b128 v[140:143], v140 offset:3072
	ds_read_b128 v[144:147], v172
	ds_read_b128 v[148:151], v172 offset:1024
	ds_read_b128 v[168:171], v172 offset:2048
	ds_read_b128 v[172:175], v172 offset:3072
	s_add_u32 s30, s38, 0xb0000
	s_addc_u32 s31, s39, 0
	s_mov_b32 m0, s43
	v_lshl_add_u64 v[226:227], s[30:31], 0, v[152:153]
	ds_read_b128 v[176:179], v191 offset:32768
	ds_read_b128 v[180:183], v191 offset:33792
	ds_read_b128 v[192:195], v191 offset:34816
	ds_read_b128 v[198:201], v191 offset:35840
	ds_read_b128 v[204:207], v191 offset:36864
	ds_read_b128 v[208:211], v191 offset:37888
	ds_read_b128 v[212:215], v191 offset:38912
	ds_read_b128 v[216:219], v191 offset:39936
	global_load_lds_dwordx4 v[226:227], off
	v_lshl_add_u64 v[226:227], s[30:31], 0, v[156:157]
	s_mov_b32 m0, s44
	s_nop 0
	global_load_lds_dwordx4 v[226:227], off
	s_waitcnt vmcnt(8)
	s_waitcnt lgkmcnt(0)
	s_barrier
	s_waitcnt lgkmcnt(0)
	v_mfma_f32_16x16x32_bf16 v[124:127], v[128:131], v[176:179], v[124:127]
	v_mfma_f32_16x16x32_bf16 v[120:123], v[136:139], v[176:179], v[120:123]
	v_mfma_f32_16x16x32_bf16 v[108:111], v[128:131], v[192:195], v[108:111]
	v_mfma_f32_16x16x32_bf16 v[104:107], v[136:139], v[192:195], v[104:107]
	v_mfma_f32_16x16x32_bf16 v[92:95], v[128:131], v[204:207], v[92:95]
	v_mfma_f32_16x16x32_bf16 v[88:91], v[136:139], v[204:207], v[88:91]
	v_mfma_f32_16x16x32_bf16 v[76:79], v[128:131], v[212:215], v[76:79]
	v_mfma_f32_16x16x32_bf16 v[72:75], v[136:139], v[212:215], v[72:75]
	v_mfma_f32_16x16x32_bf16 v[124:127], v[132:135], v[180:183], v[124:127]
	v_mfma_f32_16x16x32_bf16 v[120:123], v[140:143], v[180:183], v[120:123]
	v_mfma_f32_16x16x32_bf16 v[108:111], v[132:135], v[198:201], v[108:111]
	v_mfma_f32_16x16x32_bf16 v[104:107], v[140:143], v[198:201], v[104:107]
	v_mfma_f32_16x16x32_bf16 v[92:95], v[132:135], v[208:211], v[92:95]
	v_mfma_f32_16x16x32_bf16 v[88:91], v[140:143], v[208:211], v[88:91]
	v_mfma_f32_16x16x32_bf16 v[76:79], v[132:135], v[216:219], v[76:79]
	v_mfma_f32_16x16x32_bf16 v[72:75], v[140:143], v[216:219], v[72:75]
	v_mfma_f32_16x16x32_bf16 v[116:119], v[144:147], v[176:179], v[116:119]
	v_mfma_f32_16x16x32_bf16 v[112:115], v[168:171], v[176:179], v[112:115]
	v_mfma_f32_16x16x32_bf16 v[100:103], v[144:147], v[192:195], v[100:103]
	v_mfma_f32_16x16x32_bf16 v[96:99], v[168:171], v[192:195], v[96:99]
	v_mfma_f32_16x16x32_bf16 v[84:87], v[144:147], v[204:207], v[84:87]
	v_mfma_f32_16x16x32_bf16 v[80:83], v[168:171], v[204:207], v[80:83]
	v_mfma_f32_16x16x32_bf16 v[68:71], v[144:147], v[212:215], v[68:71]
	v_mfma_f32_16x16x32_bf16 v[64:67], v[168:171], v[212:215], v[64:67]
	v_mfma_f32_16x16x32_bf16 v[116:119], v[148:151], v[180:183], v[116:119]
	v_mfma_f32_16x16x32_bf16 v[112:115], v[172:175], v[180:183], v[112:115]
	v_mfma_f32_16x16x32_bf16 v[100:103], v[148:151], v[198:201], v[100:103]
	v_mfma_f32_16x16x32_bf16 v[96:99], v[172:175], v[198:201], v[96:99]
	v_mfma_f32_16x16x32_bf16 v[84:87], v[148:151], v[208:211], v[84:87]
	v_mfma_f32_16x16x32_bf16 v[80:83], v[172:175], v[208:211], v[80:83]
	v_mfma_f32_16x16x32_bf16 v[68:71], v[148:151], v[216:219], v[68:71]
	v_mfma_f32_16x16x32_bf16 v[64:67], v[172:175], v[216:219], v[64:67]
	s_barrier
	s_add_i32 s30, s57, s41
	v_lshl_add_u64 v[184:185], v[184:185], 0, s[24:25]
	s_mov_b32 m0, s30
	ds_read_b128 v[176:179], v191 offset:49152
	ds_read_b128 v[180:183], v191 offset:50176
	ds_read_b128 v[192:195], v191 offset:51200
	ds_read_b128 v[198:201], v191 offset:52224
	ds_read_b128 v[204:207], v191 offset:53248
	ds_read_b128 v[208:211], v191 offset:54272
	ds_read_b128 v[212:215], v191 offset:55296
	ds_read_b128 v[216:219], v191 offset:56320
	global_load_lds_dwordx4 v[184:185], off
	s_add_i32 m0, s30, 0x2000
	s_add_u32 s30, s36, 0xb0080
	v_lshl_add_u64 v[184:185], v[220:221], 0, s[24:25]
	s_addc_u32 s31, s37, 0
	s_add_i32 s36, s58, s41
	global_load_lds_dwordx4 v[184:185], off
	v_lshl_add_u64 v[184:185], s[30:31], 0, v[154:155]
	s_mov_b32 m0, s36
	s_nop 0
	global_load_lds_dwordx4 v[184:185], off
	v_lshl_add_u64 v[184:185], s[30:31], 0, v[158:159]
	s_add_i32 m0, s36, 0x2000
	s_nop 0
	global_load_lds_dwordx4 v[184:185], off
	v_lshl_add_u64 v[184:185], v[222:223], 0, s[24:25]
	s_mov_b32 m0, s46
	s_nop 0
	global_load_lds_dwordx4 v[184:185], off
	v_lshl_add_u64 v[184:185], v[224:225], 0, s[24:25]
	s_mov_b32 m0, s47
	s_nop 0
	global_load_lds_dwordx4 v[184:185], off
	s_waitcnt vmcnt(8)
	s_waitcnt lgkmcnt(0)
	s_barrier
	s_waitcnt lgkmcnt(0)
	v_mfma_f32_16x16x32_bf16 v[60:63], v[128:131], v[176:179], v[60:63]
	v_mfma_f32_16x16x32_bf16 v[56:59], v[136:139], v[176:179], v[56:59]
	v_mfma_f32_16x16x32_bf16 v[44:47], v[128:131], v[192:195], v[44:47]
	v_mfma_f32_16x16x32_bf16 v[40:43], v[136:139], v[192:195], v[40:43]
	v_mfma_f32_16x16x32_bf16 v[28:31], v[128:131], v[204:207], v[28:31]
	v_mfma_f32_16x16x32_bf16 v[24:27], v[136:139], v[204:207], v[24:27]
	v_mfma_f32_16x16x32_bf16 v[12:15], v[128:131], v[212:215], v[12:15]
	v_mfma_f32_16x16x32_bf16 v[8:11], v[136:139], v[212:215], v[8:11]
	v_mfma_f32_16x16x32_bf16 v[60:63], v[132:135], v[180:183], v[60:63]
	v_mfma_f32_16x16x32_bf16 v[56:59], v[140:143], v[180:183], v[56:59]
	v_mfma_f32_16x16x32_bf16 v[44:47], v[132:135], v[198:201], v[44:47]
	v_mfma_f32_16x16x32_bf16 v[40:43], v[140:143], v[198:201], v[40:43]
	v_mfma_f32_16x16x32_bf16 v[28:31], v[132:135], v[208:211], v[28:31]
	v_mfma_f32_16x16x32_bf16 v[24:27], v[140:143], v[208:211], v[24:27]
	v_mfma_f32_16x16x32_bf16 v[12:15], v[132:135], v[216:219], v[12:15]
	v_mfma_f32_16x16x32_bf16 v[8:11], v[140:143], v[216:219], v[8:11]
	v_mfma_f32_16x16x32_bf16 v[52:55], v[144:147], v[176:179], v[52:55]
	v_mfma_f32_16x16x32_bf16 v[48:51], v[168:171], v[176:179], v[48:51]
	v_mfma_f32_16x16x32_bf16 v[36:39], v[144:147], v[192:195], v[36:39]
	v_mfma_f32_16x16x32_bf16 v[32:35], v[168:171], v[192:195], v[32:35]
	v_mfma_f32_16x16x32_bf16 v[20:23], v[144:147], v[204:207], v[20:23]
	v_mfma_f32_16x16x32_bf16 v[16:19], v[168:171], v[204:207], v[16:19]
	v_mfma_f32_16x16x32_bf16 v[4:7], v[144:147], v[212:215], v[4:7]
	v_mfma_f32_16x16x32_bf16 v[0:3], v[168:171], v[212:215], v[0:3]
	v_mfma_f32_16x16x32_bf16 v[52:55], v[148:151], v[180:183], v[52:55]
	v_mfma_f32_16x16x32_bf16 v[48:51], v[172:175], v[180:183], v[48:51]
	v_mfma_f32_16x16x32_bf16 v[36:39], v[148:151], v[198:201], v[36:39]
	v_mfma_f32_16x16x32_bf16 v[32:35], v[172:175], v[198:201], v[32:35]
	v_mfma_f32_16x16x32_bf16 v[20:23], v[148:151], v[208:211], v[20:23]
	v_mfma_f32_16x16x32_bf16 v[16:19], v[172:175], v[208:211], v[16:19]
	v_mfma_f32_16x16x32_bf16 v[4:7], v[148:151], v[216:219], v[4:7]
	v_mfma_f32_16x16x32_bf16 v[0:3], v[172:175], v[216:219], v[0:3]
	s_barrier
	s_add_i32 s56, s56, 2
	s_add_u32 s54, s54, 0x100
	s_addc_u32 s55, s55, 0
	s_cmp_gt_u32 s56, 41
	s_mov_b64 s[30:31], s[34:35]
	s_cbranch_scc0 .LBB0_1124
	s_and_b64 vcc, exec, s[26:27]
	s_cbranch_vccz .LBB0_1127
	s_barrier
